# token-path softplus: dead denormal/inf guards of the log lowering removed (argument is in [1,2]; result identical)
# baseline (speedup 1.0000x reference)
.LBB0_342:
	v_or_b32_e32 v176, s0, v221
	s_waitcnt lgkmcnt(0)
	v_mbcnt_lo_u32_b32 v232, -1, 0
	v_mbcnt_hi_u32_b32 v232, -1, v232
	v_and_b32_e32 v233, 15, v232
	v_lshrrev_b32_e32 v234, 4, v232
	v_lshrrev_b32_e32 v198, 2, v233
	v_xor_b32_e32 v198, v198, v234
	v_lshlrev_b32_e32 v198, 4, v198
	v_lshl_or_b32 v198, v233, 6, v198
	s_lshl_b32 s100, s89, 11
	s_add_i32 s100, s100, 0x20000
	v_add_u32_e32 v198, s100, v198
	v_lshl_add_u32 v199, v232, 4, s100
	v_lshrrev_b32_e32 v202, 2, v232
	v_sub_u32_e32 v202, v202, v233
	v_mul_i32_i24_e32 v202, 0xc00, v202
	v_and_b32_e32 v203, 3, v232
	v_xor_b32_e32 v203, v203, v234
	v_sub_u32_e32 v203, v203, v234
	v_lshlrev_b32_e32 v203, 4, v203
	v_add_u32_e32 v202, v202, v203
	v_ashrrev_i32_e32 v203, 31, v202
	v_lshrrev_b32_e32 v204, 2, v232
	v_sub_u32_e32 v204, v204, v233
	v_mul_i32_i24_e32 v204, 0x200, v204
	v_and_b32_e32 v205, 3, v232
	v_xor_b32_e32 v205, v205, v234
	v_sub_u32_e32 v205, v205, v234
	v_lshlrev_b32_e32 v205, 4, v205
	v_add_u32_e32 v204, v204, v205
	v_ashrrev_i32_e32 v205, 31, v204
	v_mov_b64_e32 v[0:1], s[10:11]
	v_mad_i64_i32 v[0:1], s[4:5], v176, s86, v[0:1]
	s_mov_b64 s[4:5], 0x2040c00
	s_nop 0
	v_lshl_add_u64 v[180:181], v[0:1], 0, s[4:5]
	v_bitop3_b32 v0, s0, v241, v221 bitop3:0xc8
	v_cmp_eq_u32_e32 vcc, 0, v0
	v_mov_b32_e32 v0, 0xffffec00
	v_mov_b32_e32 v159, v195
	v_cndmask_b32_e64 v185, -1, 0, vcc
	v_cndmask_b32_e64 v184, v0, 0, vcc
	v_lshl_add_u64 v[0:1], v[180:181], 0, v[194:195]
	global_load_dwordx4 v[116:119], v[0:1], off
	v_lshl_add_u64 v[182:183], v[180:181], 0, v[184:185]
	v_lshl_add_u64 v[0:1], v[182:183], 0, v[194:195]
	global_load_dwordx4 v[186:189], v[0:1], off
	global_load_dwordx4 v[80:83], v[122:123], off offset:3072
	global_load_dwordx4 v[206:209], v[122:123], off offset:3088
	v_lshl_add_u64 v[0:1], v[180:181], 0, v[158:159]
	global_load_dwordx4 v[104:107], v[0:1], off
	v_lshl_add_u64 v[0:1], v[182:183], 0, v[158:159]
	v_mov_b32_e32 v161, v195
	global_load_dwordx4 v[84:87], v[0:1], off
	global_load_dwordx4 v[108:111], v[122:123], off offset:3216
	global_load_dwordx4 v[112:115], v[122:123], off offset:3200
	v_lshl_add_u64 v[0:1], v[180:181], 0, v[160:161]
	global_load_dwordx4 v[88:91], v[0:1], off
	v_lshl_add_u64 v[0:1], v[182:183], 0, v[160:161]
	v_mov_b32_e32 v163, v195
	global_load_dwordx4 v[92:95], v[0:1], off
	global_load_dwordx4 v[96:99], v[122:123], off offset:3328
	global_load_dwordx4 v[100:103], v[122:123], off offset:3344
	v_lshl_add_u64 v[0:1], v[180:181], 0, v[162:163]
	v_cndmask_b32_e64 v178, 1.0, 0, vcc
	global_load_dwordx4 v[64:67], v[0:1], off
	v_lshl_add_u64 v[0:1], v[182:183], 0, v[162:163]
	global_load_dwordx4 v[68:71], v[0:1], off
	global_load_dwordx4 v[72:75], v[122:123], off offset:3456
	global_load_dwordx4 v[76:79], v[122:123], off offset:3472
	global_load_dwordx4 v[60:63], v[124:125], off
	global_load_dwordx4 v[56:59], v[124:125], off offset:64
	global_load_dwordx4 v[52:55], v[124:125], off offset:128
	global_load_dwordx4 v[48:51], v[124:125], off offset:192
	global_load_dwordx4 v[44:47], v[124:125], off offset:1024
	global_load_dwordx4 v[40:43], v[124:125], off offset:1088
	global_load_dwordx4 v[28:31], v[124:125], off offset:1152
	global_load_dwordx4 v[24:27], v[124:125], off offset:1216
	global_load_dwordx4 v[20:23], v[126:127], off
	global_load_dwordx4 v[0:3], v[128:129], off
	global_load_dwordx4 v[4:7], v[130:131], off
	global_load_dwordx4 v[8:11], v[132:133], off
	global_load_dwordx4 v[12:15], v[134:135], off
	global_load_dwordx4 v[16:19], v[136:137], off
	global_load_dwordx4 v[32:35], v[138:139], off
	global_load_dwordx4 v[36:39], v[140:141], off
	v_ashrrev_i32_e32 v177, 31, v176
	v_lshlrev_b64 v[212:213], 9, v[176:177]
	v_lshl_add_u64 v[212:213], v[156:157], 0, v[212:213]
	s_waitcnt vmcnt(0) lgkmcnt(0)
	v_and_b32_e32 v163, 0xffff0000, v116
	v_lshlrev_b32_e32 v165, 16, v117
	v_and_b32_e32 v167, 0xffff0000, v117
	v_lshlrev_b32_e32 v161, 16, v118
	v_and_b32_e32 v159, 0xffff0000, v118
	v_lshlrev_b32_e32 v118, 16, v119
	v_and_b32_e32 v117, 0xffff0000, v119
	v_and_b32_e32 v119, 0xffff0000, v186
	v_lshlrev_b32_e32 v169, 16, v187
	v_fma_f32 v119, v178, v119, -v163
	v_and_b32_e32 v171, 0xffff0000, v187
	v_fmac_f32_e32 v163, v81, v119
	v_fma_f32 v81, v178, v169, -v165
	v_lshlrev_b32_e32 v173, 16, v188
	v_fmac_f32_e32 v165, v82, v81
	v_fma_f32 v81, v178, v171, -v167
	v_and_b32_e32 v175, 0xffff0000, v188
	v_fmac_f32_e32 v167, v83, v81
	v_fma_f32 v81, v178, v173, -v161
	v_lshlrev_b32_e32 v187, 16, v189
	v_fmac_f32_e32 v161, v206, v81
	v_fma_f32 v81, v178, v175, -v159
	v_and_b32_e32 v188, 0xffff0000, v189
	v_fmac_f32_e32 v159, v207, v81
	v_fma_f32 v81, v178, v187, -v118
	v_fmac_f32_e32 v118, v208, v81
	v_fma_f32 v81, v178, v188, -v117
	v_fmac_f32_e32 v117, v209, v81
	v_lshlrev_b32_e32 v81, 16, v186
	v_lshlrev_b32_e32 v82, 16, v116
	v_fma_f32 v81, v178, v81, -v82
	v_fmac_f32_e32 v82, v80, v81
	v_add_f32_e32 v80, v82, v82
	v_add_f32_e32 v81, v163, v163
	v_mul_f32_e32 v80, 0x3fb8aa3b, v80
	v_mul_f32_e32 v81, 0x3fb8aa3b, v81
	v_exp_f32_e32 v80, v80
	v_exp_f32_e32 v81, v81
	v_add_f32_e32 v117, v117, v117
	v_mul_f32_e32 v117, 0x3fb8aa3b, v117
	v_exp_f32_e32 v117, v117
	v_pk_add_f32 v[80:81], v[80:81], 1.0 op_sel_hi:[1,0]
	v_mov_b32_e32 v169, v195
	v_mov_b32_e32 v171, v195
	v_mov_b32_e32 v173, v195
	v_mov_b32_e32 v175, v195
	v_rcp_f32_e32 v81, v81
	s_nop 0
	v_mul_f32_e32 v81, 2.0, v81
	v_rcp_f32_e32 v80, v80
	s_nop 0
	v_mul_f32_e32 v80, 2.0, v80
	v_add_f32_e32 v82, v165, v165
	v_add_f32_e32 v83, v167, v167
	v_mul_f32_e32 v82, 0x3fb8aa3b, v82
	v_mul_f32_e32 v83, 0x3fb8aa3b, v83
	v_exp_f32_e32 v82, v82
	v_exp_f32_e32 v83, v83
	v_pk_add_f32 v[80:81], v[80:81], 1.0 op_sel_hi:[1,0] neg_lo:[1,0] neg_hi:[1,0]
	v_pk_add_f32 v[82:83], v[82:83], 1.0 op_sel_hi:[1,0]
	s_nop 0
	v_cvt_pk_bf16_f32 v80, v80, v81
	v_rcp_f32_e32 v83, v83
	s_nop 0
	v_mul_f32_e32 v83, 2.0, v83
	v_rcp_f32_e32 v82, v82
	s_nop 0
	v_mul_f32_e32 v82, 2.0, v82
	v_add_f32_e32 v116, v161, v161
	v_mul_f32_e32 v116, 0x3fb8aa3b, v116
	v_exp_f32_e32 v186, v116
	v_add_f32_e32 v116, v159, v159
	v_mul_f32_e32 v116, 0x3fb8aa3b, v116
	v_exp_f32_e32 v187, v116
	v_pk_add_f32 v[82:83], v[82:83], 1.0 op_sel_hi:[1,0] neg_lo:[1,0] neg_hi:[1,0]
	v_mov_b32_e32 v165, v195
	v_cvt_pk_bf16_f32 v81, v82, v83
	v_pk_add_f32 v[186:187], v[186:187], 1.0 op_sel_hi:[1,0]
	v_mov_b32_e32 v167, v195
	v_rcp_f32_e32 v187, v187
	s_nop 0
	v_mul_f32_e32 v187, 2.0, v187
	v_rcp_f32_e32 v186, v186
	s_nop 0
	v_mul_f32_e32 v186, 2.0, v186
	v_add_f32_e32 v116, v118, v118
	v_mul_f32_e32 v116, 0x3fb8aa3b, v116
	v_exp_f32_e32 v116, v116
	v_pk_add_f32 v[186:187], v[186:187], 1.0 op_sel_hi:[1,0] neg_lo:[1,0] neg_hi:[1,0]
	v_pk_add_f32 v[116:117], v[116:117], 1.0 op_sel_hi:[1,0]
	s_nop 0
	v_cvt_pk_bf16_f32 v82, v186, v187
	v_rcp_f32_e32 v117, v117
	s_nop 0
	v_mul_f32_e32 v117, 2.0, v117
	v_rcp_f32_e32 v116, v116
	s_nop 0
	v_mul_f32_e32 v116, 2.0, v116
	v_pk_add_f32 v[116:117], v[116:117], 1.0 op_sel_hi:[1,0] neg_lo:[1,0] neg_hi:[1,0]
	v_lshlrev_b32_e32 v118, 16, v84
	v_cvt_pk_bf16_f32 v83, v116, v117
	v_lshlrev_b32_e32 v116, 16, v104
	v_and_b32_e32 v117, 0xffff0000, v104
	v_and_b32_e32 v119, 0xffff0000, v84
	v_lshlrev_b32_e32 v104, 16, v105
	v_and_b32_e32 v105, 0xffff0000, v105
	v_lshlrev_b32_e32 v84, 16, v85
	v_and_b32_e32 v85, 0xffff0000, v85
	v_pk_fma_f32 v[84:85], v[178:179], v[84:85], v[104:105] op_sel_hi:[0,1,1] neg_lo:[0,0,1] neg_hi:[0,0,1]
	v_pk_fma_f32 v[104:105], v[114:115], v[84:85], v[104:105]
	v_lshlrev_b32_e32 v84, 16, v106
	v_and_b32_e32 v85, 0xffff0000, v106
	v_lshlrev_b32_e32 v114, 16, v86
	v_and_b32_e32 v115, 0xffff0000, v86
	v_pk_fma_f32 v[114:115], v[178:179], v[114:115], v[84:85] op_sel_hi:[0,1,1] neg_lo:[0,0,1] neg_hi:[0,0,1]
	v_pk_fma_f32 v[108:109], v[108:109], v[114:115], v[84:85]
	v_lshlrev_b32_e32 v84, 16, v107
	v_and_b32_e32 v85, 0xffff0000, v107
	v_lshlrev_b32_e32 v86, 16, v87
	v_and_b32_e32 v87, 0xffff0000, v87
	v_pk_fma_f32 v[86:87], v[178:179], v[86:87], v[84:85] op_sel_hi:[0,1,1] neg_lo:[0,0,1] neg_hi:[0,0,1]
	v_pk_fma_f32 v[106:107], v[110:111], v[86:87], v[84:85]
	v_cvt_pk_bf16_f32 v85, v104, v105
	v_cvt_pk_bf16_f32 v87, v106, v107
	v_and_b32_e32 v104, 0xffff0000, v88
	v_lshlrev_b32_e32 v105, 16, v89
	v_and_b32_e32 v106, 0xffff0000, v89
	v_and_b32_e32 v89, 0xffff0000, v92
	v_cvt_pk_bf16_f32 v86, v108, v109
	v_lshlrev_b32_e32 v109, 16, v93
	v_fma_f32 v89, v178, v89, -v104
	v_and_b32_e32 v93, 0xffff0000, v93
	v_fmac_f32_e32 v104, v97, v89
	v_fma_f32 v89, v178, v109, -v105
	v_lshlrev_b32_e32 v107, 16, v90
	v_lshlrev_b32_e32 v110, 16, v94
	v_fmac_f32_e32 v105, v98, v89
	v_fma_f32 v89, v178, v93, -v106
	v_and_b32_e32 v90, 0xffff0000, v90
	v_and_b32_e32 v94, 0xffff0000, v94
	v_fmac_f32_e32 v106, v99, v89
	v_fma_f32 v89, v178, v110, -v107
	v_lshlrev_b32_e32 v108, 16, v91
	v_lshlrev_b32_e32 v111, 16, v95
	v_fmac_f32_e32 v107, v100, v89
	v_fma_f32 v89, v178, v94, -v90
	v_and_b32_e32 v91, 0xffff0000, v91
	v_and_b32_e32 v95, 0xffff0000, v95
	v_fmac_f32_e32 v90, v101, v89
	v_fma_f32 v89, v178, v111, -v108
	v_fmac_f32_e32 v108, v102, v89
	v_fma_f32 v89, v178, v95, -v91
	v_fmac_f32_e32 v91, v103, v89
	v_lshlrev_b32_e32 v89, 16, v92
	v_lshlrev_b32_e32 v88, 16, v88
	v_fma_f32 v89, v178, v89, -v88
	v_fmac_f32_e32 v88, v96, v89
	v_mul_f32_e32 v88, 0xbfb8aa3b, v88
	v_mul_f32_e32 v89, 0xbfb8aa3b, v104
	v_exp_f32_e32 v88, v88
	v_exp_f32_e32 v89, v89
	v_pk_fma_f32 v[118:119], v[178:179], v[118:119], v[116:117] op_sel_hi:[0,1,1] neg_lo:[0,0,1] neg_hi:[0,0,1]
	v_pk_fma_f32 v[112:113], v[112:113], v[118:119], v[116:117]
	v_pk_add_f32 v[88:89], v[88:89], 1.0 op_sel_hi:[1,0]
	s_nop 0
	v_cvt_pk_bf16_f32 v84, v112, v113
	v_rcp_f32_e32 v92, v89
	s_nop 0
	v_mfma_f32_16x16x32_bf16 v[16:19], v[16:19], v[84:87], 0
	v_rcp_f32_e32 v93, v88
	v_mul_f32_e32 v88, 0xbfb8aa3b, v105
	v_mul_f32_e32 v89, 0xbfb8aa3b, v106
	v_exp_f32_e32 v88, v88
	v_exp_f32_e32 v89, v89
	s_nop 0
	v_pk_add_f32 v[88:89], v[88:89], 1.0 op_sel_hi:[1,0]
	s_nop 0
	v_rcp_f32_e32 v94, v89
	v_rcp_f32_e32 v95, v88
	v_mul_f32_e32 v88, 0xbfb8aa3b, v107
	v_mul_f32_e32 v89, 0xbfb8aa3b, v90
	v_exp_f32_e32 v88, v88
	v_exp_f32_e32 v89, v89
	s_nop 0
	v_pk_add_f32 v[88:89], v[88:89], 1.0 op_sel_hi:[1,0]
	s_nop 0
	v_rcp_f32_e32 v90, v89
	v_rcp_f32_e32 v96, v88
	v_mul_f32_e32 v88, 0xbfb8aa3b, v108
	v_mul_f32_e32 v89, 0xbfb8aa3b, v91
	v_exp_f32_e32 v88, v88
	v_exp_f32_e32 v89, v89
	v_cvt_pk_bf16_f32 v90, v96, v90
	v_lshlrev_b32_e32 v96, 16, v67
	v_and_b32_e32 v67, 0xffff0000, v67
	v_pk_add_f32 v[88:89], v[88:89], 1.0 op_sel_hi:[1,0]
	s_nop 0
	v_rcp_f32_e32 v91, v89
	v_rcp_f32_e32 v97, v88
	v_cvt_pk_bf16_f32 v88, v93, v92
	v_cvt_pk_bf16_f32 v89, v95, v94
	v_and_b32_e32 v92, 0xffff0000, v64
	v_lshlrev_b32_e32 v93, 16, v65
	v_and_b32_e32 v94, 0xffff0000, v65
	v_and_b32_e32 v65, 0xffff0000, v68
	v_cvt_pk_bf16_f32 v91, v97, v91
	v_lshlrev_b32_e32 v97, 16, v69
	v_fma_f32 v65, v178, v65, -v92
	v_and_b32_e32 v69, 0xffff0000, v69
	v_fmac_f32_e32 v92, v73, v65
	v_fma_f32 v65, v178, v97, -v93
	v_lshlrev_b32_e32 v95, 16, v66
	v_lshlrev_b32_e32 v98, 16, v70
	v_fmac_f32_e32 v93, v74, v65
	v_fma_f32 v65, v178, v69, -v94
	v_and_b32_e32 v66, 0xffff0000, v66
	v_and_b32_e32 v70, 0xffff0000, v70
	v_fmac_f32_e32 v94, v75, v65
	v_fma_f32 v65, v178, v98, -v95
	v_lshlrev_b32_e32 v99, 16, v71
	v_fmac_f32_e32 v95, v76, v65
	v_fma_f32 v65, v178, v70, -v66
	v_and_b32_e32 v71, 0xffff0000, v71
	v_fmac_f32_e32 v66, v77, v65
	v_fma_f32 v65, v178, v99, -v96
	v_fmac_f32_e32 v96, v78, v65
	v_fma_f32 v65, v178, v71, -v67
	v_fmac_f32_e32 v67, v79, v65
	v_lshlrev_b32_e32 v65, 16, v68
	v_lshlrev_b32_e32 v64, 16, v64
	v_fma_f32 v65, v178, v65, -v64
	v_fmac_f32_e32 v64, v72, v65
	v_mul_f32_e32 v64, 0xbfb8aa3b, v64
	v_mul_f32_e32 v65, 0xbfb8aa3b, v92
	v_exp_f32_e32 v64, v64
	v_exp_f32_e32 v65, v65
	v_mfma_f32_16x16x32_bf16 v[28:31], v[28:31], v[88:91], 0
	v_add_f32_e64 v64, v64, 1.0
	v_add_f32_e64 v65, v65, 1.0
	v_mfma_f32_16x16x32_bf16 v[52:55], v[52:55], v[88:91], 0
	v_rcp_f32_e32 v68, v65
	v_rcp_f32_e32 v69, v64
	v_mul_f32_e32 v64, 0xbfb8aa3b, v93
	v_mul_f32_e32 v65, 0xbfb8aa3b, v94
	v_exp_f32_e32 v64, v64
	v_exp_f32_e32 v65, v65
	s_nop 0
	v_pk_add_f32 v[64:65], v[64:65], 1.0 op_sel_hi:[1,0]
	s_nop 0
	v_rcp_f32_e32 v70, v65
	v_rcp_f32_e32 v71, v64
	v_mul_f32_e32 v64, 0xbfb8aa3b, v95
	v_mul_f32_e32 v65, 0xbfb8aa3b, v66
	v_exp_f32_e32 v64, v64
	v_exp_f32_e32 v65, v65
	v_mfma_f32_16x16x32_bf16 v[92:95], v[56:59], v[84:87], 0
	v_add_f32_e64 v64, v64, 1.0
	v_add_f32_e64 v65, v65, 1.0
	v_mfma_f32_16x16x32_bf16 v[56:59], v[40:43], v[84:87], 0
	v_rcp_f32_e32 v66, v65
	v_rcp_f32_e32 v72, v64
	v_mul_f32_e32 v64, 0xbfb8aa3b, v96
	v_mul_f32_e32 v65, 0xbfb8aa3b, v67
	v_exp_f32_e32 v64, v64
	v_exp_f32_e32 v65, v65
	v_cvt_pk_bf16_f32 v66, v72, v66
	v_mfma_f32_16x16x32_bf16 v[96:99], v[60:63], v[80:83], 0
	v_add_f32_e64 v64, v64, 1.0
	v_add_f32_e64 v65, v65, 1.0
	v_mfma_f32_16x16x32_bf16 v[60:63], v[44:47], v[80:83], 0
	v_rcp_f32_e32 v67, v65
	v_rcp_f32_e32 v73, v64
	v_cvt_pk_bf16_f32 v64, v69, v68
	v_cvt_pk_bf16_f32 v65, v71, v70
	v_cvt_pk_bf16_f32 v67, v73, v67
	s_nop 1
	v_mfma_f32_16x16x32_bf16 v[40:43], v[24:27], v[64:67], v[28:31]
	v_mfma_f32_16x16x32_bf16 v[24:27], v[0:3], v[84:87], 0
	v_mfma_f32_16x16x32_bf16 v[0:3], v[4:7], v[88:91], 0
	v_mfma_f32_16x16x32_bf16 v[0:3], v[8:11], v[64:67], v[0:3]
	v_lshl_add_u64 v[8:9], v[180:181], 0, v[164:165]
	global_load_dwordx4 v[186:189], v[8:9], off
	v_lshl_add_u64 v[8:9], v[8:9], 0, v[184:185]
	v_mfma_f32_16x16x32_bf16 v[4:7], v[32:35], v[88:91], 0
	global_load_dwordx4 v[216:219], v[8:9], off
	global_load_dwordx4 v[222:225], v[142:143], off offset:16
	global_load_dwordx4 v[208:211], v[142:143], off
	v_lshl_add_u64 v[8:9], v[180:181], 0, v[166:167]
	global_load_dwordx4 v[72:75], v[8:9], off
	v_lshl_add_u64 v[8:9], v[182:183], 0, v[166:167]
	v_mfma_f32_16x16x32_bf16 v[48:51], v[48:51], v[64:67], v[52:55]
	v_cvt_pk_bf16_f32 v0, v0, v1
	v_cvt_pk_bf16_f32 v1, v2, v3
	s_waitcnt vmcnt(0) lgkmcnt(0)
	v_lshlrev_b32_e32 v184, 16, v186
	v_mfma_f32_16x16x32_bf16 v[4:7], v[36:39], v[64:67], v[4:7]
	global_load_dwordx4 v[68:71], v[8:9], off
	global_load_dwordx4 v[64:67], v[142:143], off offset:1040
	global_load_dwordx4 v[100:103], v[142:143], off offset:1024
	v_lshl_add_u64 v[8:9], v[180:181], 0, v[168:169]
	global_load_dwordx4 v[44:47], v[8:9], off
	v_lshl_add_u64 v[8:9], v[182:183], 0, v[168:169]
	v_mfma_f32_16x16x32_bf16 v[28:31], v[20:23], v[80:83], 0
	v_and_b32_e32 v185, 0xffff0000, v186
	v_lshlrev_b32_e32 v190, 16, v216
	v_and_b32_e32 v191, 0xffff0000, v216
	v_mfma_f32_16x16x32_bf16 v[20:23], v[12:15], v[80:83], 0
	global_load_dwordx4 v[36:39], v[8:9], off
	global_load_dwordx4 v[32:35], v[142:143], off offset:2064
	global_load_dwordx4 v[52:55], v[142:143], off offset:2048
	global_load_dwordx4 v[84:87], v[144:145], off offset:16
	global_load_dwordx4 v[116:119], v[144:145], off
	global_load_dwordx4 v[88:91], v[146:147], off offset:16
	global_load_dwordx4 v[112:115], v[146:147], off
	global_load_dwordx4 v[8:11], v[148:149], off
	global_load_dwordx4 v[12:15], v[148:149], off offset:16
	global_load_dwordx4 v[80:83], v[150:151], off offset:16
	global_load_dwordx4 v[108:111], v[150:151], off
	global_load_dwordx4 v[76:79], v[152:153], off offset:16
	global_load_dwordx4 v[104:107], v[152:153], off
	v_pk_fma_f32 v[190:191], v[178:179], v[190:191], v[184:185] op_sel_hi:[0,1,1] neg_lo:[0,0,1] neg_hi:[0,0,1]
	v_pk_fma_f32 v[208:209], v[208:209], v[190:191], v[184:185]
	v_lshlrev_b32_e32 v184, 16, v187
	v_and_b32_e32 v185, 0xffff0000, v187
	v_lshlrev_b32_e32 v186, 16, v217
	v_and_b32_e32 v187, 0xffff0000, v217
	v_pk_fma_f32 v[186:187], v[178:179], v[186:187], v[184:185] op_sel_hi:[0,1,1] neg_lo:[0,0,1] neg_hi:[0,0,1]
	v_pk_fma_f32 v[214:215], v[210:211], v[186:187], v[184:185]
	v_lshlrev_b32_e32 v184, 16, v188
	v_and_b32_e32 v185, 0xffff0000, v188
	v_lshlrev_b32_e32 v186, 16, v218
	v_and_b32_e32 v187, 0xffff0000, v218
	v_pk_fma_f32 v[186:187], v[178:179], v[186:187], v[184:185] op_sel_hi:[0,1,1] neg_lo:[0,0,1] neg_hi:[0,0,1]
	v_pk_fma_f32 v[216:217], v[222:223], v[186:187], v[184:185]
	v_lshlrev_b32_e32 v184, 16, v189
	v_and_b32_e32 v185, 0xffff0000, v189
	v_lshlrev_b32_e32 v186, 16, v219
	v_and_b32_e32 v187, 0xffff0000, v219
	v_pk_fma_f32 v[186:187], v[178:179], v[186:187], v[184:185] op_sel_hi:[0,1,1] neg_lo:[0,0,1] neg_hi:[0,0,1]
	v_pk_fma_f32 v[218:219], v[224:225], v[186:187], v[184:185]
	v_cvt_pk_bf16_f32 v2, v4, v5
	v_cvt_pk_bf16_f32 v3, v6, v7
	s_waitcnt vmcnt(0)
	v_add_f32_e32 v60, v60, v84
	v_add_f32_e32 v96, v96, v116
	v_max_f32_e64 v116, -v96, 0
	v_mul_f32_e64 v96, |v96|, s26
	v_exp_f32_e32 v96, v96
	v_add_f32_e32 v97, v97, v117
	v_add_f32_e32 v92, v92, v112
	v_max_f32_e64 v112, -v97, 0
	v_add_f32_e32 v96, 1.0, v96
	v_mul_f32_e64 v97, |v97|, s26
	v_exp_f32_e32 v97, v97
	v_log_f32_e32 v96, v96
	v_add_f32_e32 v97, 1.0, v97
	v_add_f32_e32 v93, v93, v113
	v_mul_f32_e32 v92, 0xbfb8aa3b, v92
	v_mul_f32_e32 v159, 0x3f317217, v96
	v_fma_f32 v159, v96, s34, -v159
	v_fmac_f32_e32 v159, 0x3377d1cf, v96
	v_fmac_f32_e32 v159, 0x3f317217, v96
	v_mul_f32_e32 v93, 0xbfb8aa3b, v93
	v_exp_f32_e32 v92, v92
	v_mov_b32_e32 v96, v159
	v_add_f32_e32 v96, v116, v96
	v_exp_f32_e32 v93, v93
	v_log_f32_e32 v97, v97
	v_pk_add_f32 v[92:93], v[92:93], 1.0 op_sel_hi:[1,0]
	s_waitcnt lgkmcnt(0)
	v_and_b32_e32 v117, 0xffff0000, v68
	v_and_b32_e32 v113, 0xffff0000, v72
	v_mul_f32_e32 v116, 0x3f317217, v97
	v_fma_f32 v116, v97, s34, -v116
	v_fmac_f32_e32 v116, 0x3377d1cf, v97
	v_fmac_f32_e32 v116, 0x3f317217, v97
	v_add_f32_e32 v61, v61, v85
	v_add_f32_e32 v56, v56, v88
	v_mov_b32_e32 v97, v116
	v_lshlrev_b32_e32 v116, 16, v68
	v_add_f32_e32 v97, v112, v97
	v_lshlrev_b32_e32 v112, 16, v72
	v_pk_fma_f32 v[116:117], v[178:179], v[116:117], v[112:113] op_sel_hi:[0,1,1] neg_lo:[0,0,1] neg_hi:[0,0,1]
	v_pk_fma_f32 v[184:185], v[100:101], v[116:117], v[112:113]
	v_add_f32_e32 v57, v57, v89
	v_rcp_f32_e32 v117, v93
	v_mul_f32_e32 v56, 0xbfb8aa3b, v56
	v_mul_f32_e32 v57, 0xbfb8aa3b, v57
	v_exp_f32_e32 v56, v56
	v_rcp_f32_e32 v116, v92
	v_add_f32_e32 v68, v98, v118
	v_max_f32_e64 v72, -v68, 0
	v_mul_f32_e64 v68, |v68|, s26
	v_exp_f32_e32 v68, v68
	v_pk_add_f32 v[92:93], v[116:117], -1.0 op_sel_hi:[1,0]
	v_exp_f32_e32 v57, v57
	v_pk_fma_f32 v[92:93], v[108:109], v[92:93], 1.0 op_sel_hi:[1,1,0]
	v_add_f32_e32 v68, 1.0, v68
	v_pk_mul_f32 v[92:93], v[184:185], v[92:93]
	v_and_b32_e32 v85, 0xffff0000, v74
	v_log_f32_e32 v68, v68
	v_pk_mul_f32 v[100:101], v[208:209], v[92:93]
	v_lshlrev_b32_e32 v88, 16, v70
	v_fma_f32 v159, v104, v100, 0
	v_mul_f32_e32 v98, 0x3f317217, v68
	v_fma_f32 v98, v68, s34, -v98
	v_fmac_f32_e32 v98, 0x3377d1cf, v68
	v_fmac_f32_e32 v98, 0x3f317217, v68
	v_fmac_f32_e32 v159, v105, v101
	v_lshlrev_b32_e32 v100, 16, v73
	v_mov_b32_e32 v68, v98
	v_add_f32_e32 v68, v72, v68
	v_sub_f32_e32 v68, -0.5, v68
	v_mul_f32_e32 v68, 0x3fb8aa3b, v68
	v_exp_f32_e32 v68, v68
	v_and_b32_e32 v101, 0xffff0000, v73
	v_and_b32_e32 v89, 0xffff0000, v70
	v_pk_add_f32 v[56:57], v[56:57], 1.0 op_sel_hi:[1,0]
	v_xor_b32_e32 v72, 0x80000000, v68
	v_add_f32_e32 v68, v94, v114
	v_mul_f32_e32 v68, 0xbfb8aa3b, v68
	v_exp_f32_e32 v98, v68
	v_add_f32_e32 v68, v99, v119
	v_max_f32_e64 v94, -v68, 0
	v_mul_f32_e64 v68, |v68|, s26
	v_exp_f32_e32 v68, v68
	v_add_f32_e32 v62, v62, v86
	v_add_f32_e32 v58, v58, v90
	v_add_f32_e32 v59, v59, v91
	v_add_f32_e32 v68, 1.0, v68
	v_mul_f32_e32 v58, 0xbfb8aa3b, v58
	v_mul_f32_e32 v59, 0xbfb8aa3b, v59
	v_log_f32_e32 v68, v68
	v_exp_f32_e32 v58, v58
	v_exp_f32_e32 v59, v59
	v_sub_f32_e32 v96, -0.5, v96
	v_mul_f32_e32 v99, 0x3f317217, v68
	v_fma_f32 v99, v68, s34, -v99
	v_fmac_f32_e32 v99, 0x3377d1cf, v68
	v_fmac_f32_e32 v99, 0x3f317217, v68
	v_pk_add_f32 v[58:59], v[58:59], 1.0 op_sel_hi:[1,0]
	v_sub_f32_e32 v97, -0.5, v97
	v_mov_b32_e32 v68, v99
	v_add_f32_e32 v68, v94, v68
	v_sub_f32_e32 v68, -0.5, v68
	v_mul_f32_e32 v68, 0x3fb8aa3b, v68
	v_exp_f32_e32 v68, v68
	v_mul_f32_e32 v96, 0x3fb8aa3b, v96
	v_mul_f32_e32 v97, 0x3fb8aa3b, v97
	v_exp_f32_e32 v96, v96
	v_xor_b32_e32 v94, 0x80000000, v68
	v_add_f32_e32 v68, v95, v115
	v_mul_f32_e32 v68, 0xbfb8aa3b, v68
	v_exp_f32_e32 v99, v68
	v_lshlrev_b32_e32 v68, 16, v69
	v_and_b32_e32 v69, 0xffff0000, v69
	v_pk_fma_f32 v[68:69], v[178:179], v[68:69], v[100:101] op_sel_hi:[0,1,1] neg_lo:[0,0,1] neg_hi:[0,0,1]
	v_pk_fma_f32 v[186:187], v[102:103], v[68:69], v[100:101]
	v_pk_add_f32 v[68:69], v[98:99], 1.0 op_sel_hi:[1,0]
	v_exp_f32_e32 v97, v97
	v_xor_b32_e32 v96, 0x80000000, v96
	v_xor_b32_e32 v97, 0x80000000, v97
	v_pk_mul_f32 v[8:9], v[184:185], v[8:9]
	v_rcp_f32_e32 v119, v69
	v_pk_mul_f32 v[10:11], v[186:187], v[10:11]
	v_max_f32_e64 v73, -v60, 0
	v_mul_f32_e64 v60, |v60|, s26
	v_exp_f32_e32 v60, v60
	v_rcp_f32_e32 v118, v68
	s_nop 0
	v_pk_add_f32 v[68:69], v[118:119], -1.0 op_sel_hi:[1,0]
	v_add_f32_e32 v60, 1.0, v60
	v_pk_fma_f32 v[68:69], v[110:111], v[68:69], 1.0 op_sel_hi:[1,1,0]
	s_nop 0
	v_log_f32_e32 v60, v60
	v_pk_mul_f32 v[68:69], v[186:187], v[68:69]
	v_mul_f32_e32 v84, 0x3f317217, v60
	v_fma_f32 v84, v60, s34, -v84
	v_fmac_f32_e32 v84, 0x3377d1cf, v60
	v_fmac_f32_e32 v84, 0x3f317217, v60
	v_pk_mul_f32 v[98:99], v[214:215], v[68:69]
	s_nop 0
	v_mov_b32_e32 v60, v84
	v_add_f32_e32 v60, v73, v60
	v_max_f32_e64 v73, -v61, 0
	v_mul_f32_e64 v61, |v61|, s26
	v_exp_f32_e32 v61, v61
	v_fmac_f32_e32 v159, v106, v98
	v_fmac_f32_e32 v159, v107, v99
	v_sub_f32_e32 v60, -0.5, v60
	v_add_f32_e32 v61, 1.0, v61
	v_mul_f32_e32 v60, 0x3fb8aa3b, v60
	v_exp_f32_e32 v60, v60
	v_log_f32_e32 v61, v61
	v_xor_b32_e32 v60, 0x80000000, v60
	v_mul_f32_e32 v84, 0x3f317217, v61
	v_fma_f32 v84, v61, s34, -v84
	v_fmac_f32_e32 v84, 0x3377d1cf, v61
	v_fmac_f32_e32 v84, 0x3f317217, v61
	s_nop 1
	v_mov_b32_e32 v61, v84
	v_lshlrev_b32_e32 v84, 16, v74
	v_pk_fma_f32 v[88:89], v[178:179], v[88:89], v[84:85] op_sel_hi:[0,1,1] neg_lo:[0,0,1] neg_hi:[0,0,1]
	v_pk_fma_f32 v[190:191], v[64:65], v[88:89], v[84:85]
	v_add_f32_e32 v61, v73, v61
	v_sub_f32_e32 v61, -0.5, v61
	v_mul_f32_e32 v61, 0x3fb8aa3b, v61
	v_rcp_f32_e32 v189, v57
	v_exp_f32_e32 v61, v61
	v_pk_mul_f32 v[6:7], v[190:191], v[12:13]
	v_rcp_f32_e32 v188, v56
	s_nop 0
	v_pk_add_f32 v[56:57], v[188:189], -1.0 op_sel_hi:[1,0]
	v_xor_b32_e32 v61, 0x80000000, v61
	v_pk_fma_f32 v[56:57], v[80:81], v[56:57], 1.0 op_sel_hi:[1,1,0]
	v_pk_mul_f32 v[12:13], v[6:7], v[6:7]
	v_pk_mul_f32 v[56:57], v[190:191], v[56:57]
	s_nop 0
	v_pk_mul_f32 v[64:65], v[216:217], v[56:57]
	s_nop 0
	v_fmac_f32_e32 v159, v76, v64
	v_max_f32_e64 v64, -v62, 0
	v_mul_f32_e64 v62, |v62|, s26
	v_exp_f32_e32 v62, v62
	v_fmac_f32_e32 v159, v77, v65
	v_add_f32_e32 v62, 1.0, v62
	s_nop 1
	v_log_f32_e32 v62, v62
	s_nop 0
	v_mul_f32_e32 v65, 0x3f317217, v62
	v_fma_f32 v65, v62, s34, -v65
	v_fmac_f32_e32 v65, 0x3377d1cf, v62
	v_fmac_f32_e32 v65, 0x3f317217, v62
	s_nop 1
	v_mov_b32_e32 v62, v65
	v_add_f32_e32 v62, v64, v62
	v_sub_f32_e32 v62, -0.5, v62
	v_mul_f32_e32 v62, 0x3fb8aa3b, v62
	v_exp_f32_e32 v62, v62
	v_and_b32_e32 v65, 0xffff0000, v71
	v_xor_b32_e32 v70, 0x80000000, v62
	v_add_f32_e32 v62, v63, v87
	v_max_f32_e64 v63, -v62, 0
	v_mul_f32_e64 v62, |v62|, s26
	v_exp_f32_e32 v62, v62
	s_nop 0
	v_add_f32_e32 v62, 1.0, v62
	s_nop 1
	v_log_f32_e32 v62, v62
	s_nop 0
	v_mul_f32_e32 v64, 0x3f317217, v62
	v_fma_f32 v64, v62, s34, -v64
	v_fmac_f32_e32 v64, 0x3377d1cf, v62
	v_fmac_f32_e32 v64, 0x3f317217, v62
	s_nop 1
	v_mov_b32_e32 v62, v64
	v_add_f32_e32 v62, v63, v62
	v_sub_f32_e32 v62, -0.5, v62
	v_mul_f32_e32 v62, 0x3fb8aa3b, v62
	v_exp_f32_e32 v62, v62
	v_and_b32_e32 v63, 0xffff0000, v75
	v_lshlrev_b32_e32 v64, 16, v71
	v_xor_b32_e32 v73, 0x80000000, v62
	v_lshlrev_b32_e32 v62, 16, v75
	v_pk_fma_f32 v[64:65], v[178:179], v[64:65], v[62:63] op_sel_hi:[0,1,1] neg_lo:[0,0,1] neg_hi:[0,0,1]
	v_pk_fma_f32 v[210:211], v[66:67], v[64:65], v[62:63]
	v_rcp_f32_e32 v207, v59
	v_rcp_f32_e32 v206, v58
	s_nop 0
	v_pk_add_f32 v[58:59], v[206:207], -1.0 op_sel_hi:[1,0]
	v_lshlrev_b32_e32 v64, 16, v36
	v_pk_fma_f32 v[58:59], v[82:83], v[58:59], 1.0 op_sel_hi:[1,1,0]
	v_and_b32_e32 v65, 0xffff0000, v36
	v_pk_mul_f32 v[58:59], v[210:211], v[58:59]
	v_lshlrev_b32_e32 v36, 16, v37
	v_pk_mul_f32 v[62:63], v[218:219], v[58:59]
	v_and_b32_e32 v37, 0xffff0000, v37
	v_fmac_f32_e32 v159, v78, v62
	v_fmac_f32_e32 v159, v79, v63
	v_lshlrev_b32_e32 v62, 16, v44
	v_and_b32_e32 v63, 0xffff0000, v44
	v_lshlrev_b32_e32 v44, 16, v45
	v_and_b32_e32 v45, 0xffff0000, v45
	v_pk_fma_f32 v[36:37], v[178:179], v[36:37], v[44:45] op_sel_hi:[0,1,1] neg_lo:[0,0,1] neg_hi:[0,0,1]
	v_pk_fma_f32 v[36:37], v[54:55], v[36:37], v[44:45]
	v_lshlrev_b32_e32 v44, 16, v46
	v_and_b32_e32 v45, 0xffff0000, v46
	v_lshlrev_b32_e32 v54, 16, v38
	v_and_b32_e32 v55, 0xffff0000, v38
	v_pk_fma_f32 v[54:55], v[178:179], v[54:55], v[44:45] op_sel_hi:[0,1,1] neg_lo:[0,0,1] neg_hi:[0,0,1]
	v_pk_fma_f32 v[44:45], v[32:33], v[54:55], v[44:45]
	v_lshlrev_b32_e32 v32, 16, v47
	v_and_b32_e32 v33, 0xffff0000, v47
	v_lshlrev_b32_e32 v38, 16, v39
	v_and_b32_e32 v39, 0xffff0000, v39
	v_pk_fma_f32 v[38:39], v[178:179], v[38:39], v[32:33] op_sel_hi:[0,1,1] neg_lo:[0,0,1] neg_hi:[0,0,1]
	v_pk_fma_f32 v[64:65], v[178:179], v[64:65], v[62:63] op_sel_hi:[0,1,1] neg_lo:[0,0,1] neg_hi:[0,0,1]
	v_pk_fma_f32 v[38:39], v[34:35], v[38:39], v[32:33]
	v_cvt_pk_bf16_f32 v32, v208, v209
	v_cvt_pk_bf16_f32 v33, v214, v215
	v_cvt_pk_bf16_f32 v34, v216, v217
	v_cvt_pk_bf16_f32 v35, v218, v219
	v_mad_i64_i32 v[208:209], s[0:1], v176, s23, v[154:155]
	v_pk_fma_f32 v[52:53], v[52:53], v[64:65], v[62:63]
	ds_write_b128 v198, v[32:35]
	ds_read_b128 v[232:235], v199
	v_lshl_add_u64 v[230:231], v[208:209], 0, v[202:203]
	s_nop 1
	v_cvt_pk_bf16_f32 v32, v92, v93
	v_cvt_pk_bf16_f32 v33, v68, v69
	v_cvt_pk_bf16_f32 v34, v56, v57
	v_cvt_pk_bf16_f32 v35, v58, v59
	ds_write_b128 v198, v[32:35] offset:1024
	ds_read_b128 v[246:249], v199 offset:1024
	v_lshl_add_u64 v[250:251], v[208:209], 0, v[202:203]
	s_waitcnt lgkmcnt(2)
	global_store_dwordx4 v[230:231], v[232:235], off
	s_nop 1
	v_cvt_pk_bf16_f32 v32, v52, v53
	v_cvt_pk_bf16_f32 v33, v36, v37
	v_cvt_pk_bf16_f32 v34, v44, v45
	v_cvt_pk_bf16_f32 v35, v38, v39
	ds_write_b128 v198, v[32:35]
	ds_read_b128 v[232:235], v199
	v_lshl_add_u64 v[230:231], v[208:209], 0, v[202:203]
	s_waitcnt lgkmcnt(2)
	global_store_dwordx4 v[250:251], v[246:249], off offset:512
	s_nop 1
	v_cvt_pk_bf16_f32 v32, v96, v97
	v_cvt_pk_bf16_f32 v33, v72, v94
	v_cvt_pk_bf16_f32 v34, v60, v61
	v_cvt_pk_bf16_f32 v35, v70, v73
	ds_write_b128 v198, v[32:35] offset:1024
	ds_read_b128 v[246:249], v199 offset:1024
	v_lshl_add_u64 v[250:251], v[208:209], 0, v[202:203]
	s_waitcnt lgkmcnt(2)
	global_store_dwordx4 v[230:231], v[232:235], off offset:1024
	s_nop 1
	v_cvt_pk_bf16_f32 v32, v48, v49
	v_cvt_pk_bf16_f32 v33, v50, v51
	v_cvt_pk_bf16_f32 v34, v40, v41
	v_cvt_pk_bf16_f32 v35, v42, v43
	ds_write_b128 v198, v[32:35]
	ds_read_b128 v[232:235], v199
	v_lshl_add_u64 v[230:231], v[212:213], 0, v[204:205]
	s_waitcnt lgkmcnt(2)
	global_store_dwordx4 v[250:251], v[246:249], off offset:2560
	s_nop 1
	v_lshl_add_u64 v[32:33], v[180:181], 0, v[170:171]
	global_load_dwordx4 v[108:111], v[32:33], off
	v_lshl_add_u64 v[32:33], v[182:183], 0, v[170:171]
	global_load_dwordx4 v[112:115], v[32:33], off
	global_load_dwordx4 v[104:107], v[142:143], off offset:144
	global_load_dwordx4 v[214:217], v[142:143], off offset:128
	v_lshl_add_u64 v[32:33], v[180:181], 0, v[172:173]
	global_load_dwordx4 v[60:63], v[32:33], off
	v_lshl_add_u64 v[32:33], v[182:183], 0, v[172:173]
	global_load_dwordx4 v[56:59], v[32:33], off
	global_load_dwordx4 v[52:55], v[142:143], off offset:1168
	global_load_dwordx4 v[84:87], v[142:143], off offset:1152
	v_lshl_add_u64 v[32:33], v[180:181], 0, v[174:175]
	global_load_dwordx4 v[40:43], v[32:33], off
	v_lshl_add_u64 v[32:33], v[182:183], 0, v[174:175]
	global_load_dwordx4 v[36:39], v[32:33], off
	s_nop 0
	global_load_dwordx4 v[32:35], v[142:143], off offset:2192
	global_load_dwordx4 v[44:47], v[142:143], off offset:2176
	global_load_dwordx4 v[64:67], v[144:145], off offset:144
	global_load_dwordx4 v[96:99], v[144:145], off offset:128
	global_load_dwordx4 v[80:83], v[146:147], off offset:144
	global_load_dwordx4 v[100:103], v[146:147], off offset:128
	global_load_dwordx4 v[68:71], v[148:149], off offset:144
	global_load_dwordx4 v[48:51], v[148:149], off offset:128
	global_load_dwordx4 v[76:79], v[150:151], off offset:144
	global_load_dwordx4 v[92:95], v[150:151], off offset:128
	global_load_dwordx4 v[72:75], v[152:153], off offset:144
	global_load_dwordx4 v[88:91], v[152:153], off offset:128
	s_waitcnt vmcnt(0) lgkmcnt(0)
	v_lshlrev_b32_e32 v180, 16, v108
	v_and_b32_e32 v181, 0xffff0000, v108
	v_add_f32_e32 v28, v28, v96
	v_max_f32_e64 v96, -v28, 0
	v_mul_f32_e64 v28, |v28|, s26
	v_lshlrev_b32_e32 v182, 16, v112
	v_and_b32_e32 v183, 0xffff0000, v112
	v_lshlrev_b32_e32 v108, 16, v109
	v_and_b32_e32 v109, 0xffff0000, v109
	v_lshlrev_b32_e32 v112, 16, v113
	v_and_b32_e32 v113, 0xffff0000, v113
	v_exp_f32_e32 v28, v28
	v_pk_fma_f32 v[182:183], v[178:179], v[182:183], v[180:181] op_sel_hi:[0,1,1] neg_lo:[0,0,1] neg_hi:[0,0,1]
	v_pk_fma_f32 v[112:113], v[178:179], v[112:113], v[108:109] op_sel_hi:[0,1,1] neg_lo:[0,0,1] neg_hi:[0,0,1]
	v_pk_fma_f32 v[180:181], v[214:215], v[182:183], v[180:181]
	v_pk_fma_f32 v[108:109], v[216:217], v[112:113], v[108:109]
	v_lshlrev_b32_e32 v112, 16, v110
	v_and_b32_e32 v113, 0xffff0000, v110
	v_lshlrev_b32_e32 v182, 16, v114
	v_and_b32_e32 v183, 0xffff0000, v114
	v_pk_fma_f32 v[182:183], v[178:179], v[182:183], v[112:113] op_sel_hi:[0,1,1] neg_lo:[0,0,1] neg_hi:[0,0,1]
	v_pk_fma_f32 v[104:105], v[104:105], v[182:183], v[112:113]
	v_lshlrev_b32_e32 v110, 16, v111
	v_and_b32_e32 v111, 0xffff0000, v111
	v_lshlrev_b32_e32 v112, 16, v115
	v_and_b32_e32 v113, 0xffff0000, v115
	v_add_f32_e32 v28, 1.0, v28
	v_pk_fma_f32 v[112:113], v[178:179], v[112:113], v[110:111] op_sel_hi:[0,1,1] neg_lo:[0,0,1] neg_hi:[0,0,1]
	v_pk_fma_f32 v[106:107], v[106:107], v[112:113], v[110:111]
	v_add_f32_e32 v24, v24, v100
	v_log_f32_e32 v28, v28
	v_add_f32_e32 v25, v25, v101
	v_mul_f32_e32 v24, 0xbfb8aa3b, v24
	v_mul_f32_e32 v25, 0xbfb8aa3b, v25
	v_mul_f32_e32 v110, 0x3f317217, v28
	v_fma_f32 v110, v28, s34, -v110
	v_fmac_f32_e32 v110, 0x3377d1cf, v28
	v_fmac_f32_e32 v110, 0x3f317217, v28
	v_exp_f32_e32 v24, v24
	v_exp_f32_e32 v25, v25
	v_mov_b32_e32 v28, v110
	v_add_f32_e32 v28, v96, v28
	v_sub_f32_e32 v28, -0.5, v28
	v_mul_f32_e32 v28, 0x3fb8aa3b, v28
	v_exp_f32_e32 v28, v28
	v_pk_add_f32 v[24:25], v[24:25], 1.0 op_sel_hi:[1,0]
	v_lshlrev_b32_e32 v100, 16, v56
	v_and_b32_e32 v101, 0xffff0000, v56
	v_xor_b32_e32 v96, 0x80000000, v28
	v_add_f32_e32 v28, v29, v97
	v_max_f32_e64 v29, -v28, 0
	v_mul_f32_e64 v28, |v28|, s26
	v_exp_f32_e32 v28, v28
	v_add_f32_e32 v30, v30, v98
	v_add_f32_e32 v26, v26, v102
	v_add_f32_e32 v27, v27, v103
	v_add_f32_e32 v28, 1.0, v28
	v_mul_f32_e32 v26, 0xbfb8aa3b, v26
	v_mul_f32_e32 v27, 0xbfb8aa3b, v27
	v_log_f32_e32 v28, v28
	v_exp_f32_e32 v26, v26
	v_exp_f32_e32 v27, v27
	v_add_f32_e32 v20, v20, v64
	v_mul_f32_e32 v97, 0x3f317217, v28
	v_fma_f32 v97, v28, s34, -v97
	v_fmac_f32_e32 v97, 0x3377d1cf, v28
	v_fmac_f32_e32 v97, 0x3f317217, v28
	v_pk_add_f32 v[26:27], v[26:27], 1.0 op_sel_hi:[1,0]
	v_add_f32_e32 v16, v16, v80
	v_mov_b32_e32 v28, v97
	v_add_f32_e32 v28, v29, v28
	v_sub_f32_e32 v28, -0.5, v28
	v_mul_f32_e32 v28, 0x3fb8aa3b, v28
	v_exp_f32_e32 v28, v28
	v_and_b32_e32 v29, 0xffff0000, v60
	v_xor_b32_e32 v97, 0x80000000, v28
	v_lshlrev_b32_e32 v28, 16, v60
	v_pk_fma_f32 v[100:101], v[178:179], v[100:101], v[28:29] op_sel_hi:[0,1,1] neg_lo:[0,0,1] neg_hi:[0,0,1]
	v_pk_fma_f32 v[28:29], v[84:85], v[100:101], v[28:29]
	v_add_f32_e32 v17, v17, v81
	v_rcp_f32_e32 v25, v25
	v_mul_f32_e32 v16, 0xbfb8aa3b, v16
	v_mul_f32_e32 v17, 0xbfb8aa3b, v17
	v_exp_f32_e32 v16, v16
	v_rcp_f32_e32 v24, v24
	v_max_f32_e64 v56, -v30, 0
	v_mul_f32_e64 v30, |v30|, s26
	v_exp_f32_e32 v30, v30
	v_pk_add_f32 v[84:85], v[24:25], -1.0 op_sel_hi:[1,0]
	v_exp_f32_e32 v17, v17
	v_pk_fma_f32 v[84:85], v[92:93], v[84:85], 1.0 op_sel_hi:[1,1,0]
	v_add_f32_e32 v30, 1.0, v30
	v_pk_mul_f32 v[84:85], v[28:29], v[84:85]
	v_pk_add_f32 v[16:17], v[16:17], 1.0 op_sel_hi:[1,0]
	v_log_f32_e32 v30, v30
	v_pk_mul_f32 v[92:93], v[180:181], v[84:85]
	v_add_f32_e32 v22, v22, v66
	v_fmac_f32_e32 v159, v88, v92
	v_mul_f32_e32 v60, 0x3f317217, v30
	v_fma_f32 v60, v30, s34, -v60
	v_fmac_f32_e32 v60, 0x3377d1cf, v30
	v_fmac_f32_e32 v60, 0x3f317217, v30
	v_fmac_f32_e32 v159, v89, v93
	v_add_f32_e32 v18, v18, v82
	v_mov_b32_e32 v30, v60
	v_add_f32_e32 v30, v56, v30
	v_sub_f32_e32 v30, -0.5, v30
	v_mul_f32_e32 v30, 0x3fb8aa3b, v30
	v_exp_f32_e32 v30, v30
	v_add_f32_e32 v19, v19, v83
	v_mul_f32_e32 v18, 0xbfb8aa3b, v18
	v_mul_f32_e32 v19, 0xbfb8aa3b, v19
	v_xor_b32_e32 v88, 0x80000000, v30
	v_add_f32_e32 v30, v31, v99
	v_max_f32_e64 v31, -v30, 0
	v_mul_f32_e64 v30, |v30|, s26
	v_exp_f32_e32 v30, v30
	v_exp_f32_e32 v18, v18
	v_exp_f32_e32 v19, v19
	v_lshlrev_b32_e32 v66, 16, v36
	v_add_f32_e32 v30, 1.0, v30
	v_pk_add_f32 v[18:19], v[18:19], 1.0 op_sel_hi:[1,0]
	v_pk_mul_f32 v[28:29], v[28:29], v[48:49]
	v_log_f32_e32 v30, v30
	s_nop 0
	v_mul_f32_e32 v56, 0x3f317217, v30
	v_fma_f32 v56, v30, s34, -v56
	v_fmac_f32_e32 v56, 0x3377d1cf, v30
	v_fmac_f32_e32 v56, 0x3f317217, v30
	s_nop 1
	v_mov_b32_e32 v30, v56
	v_add_f32_e32 v30, v31, v30
	v_sub_f32_e32 v30, -0.5, v30
	v_mul_f32_e32 v30, 0x3fb8aa3b, v30
	v_exp_f32_e32 v30, v30
	v_and_b32_e32 v31, 0xffff0000, v61
	v_lshlrev_b32_e32 v56, 16, v57
	v_and_b32_e32 v57, 0xffff0000, v57
	v_xor_b32_e32 v89, 0x80000000, v30
	v_lshlrev_b32_e32 v30, 16, v61
	v_pk_fma_f32 v[56:57], v[178:179], v[56:57], v[30:31] op_sel_hi:[0,1,1] neg_lo:[0,0,1] neg_hi:[0,0,1]
	v_pk_fma_f32 v[30:31], v[86:87], v[56:57], v[30:31]
	v_rcp_f32_e32 v27, v27
	v_rcp_f32_e32 v26, v26
	s_nop 0
	v_pk_add_f32 v[56:57], v[26:27], -1.0 op_sel_hi:[1,0]
	s_nop 0
	v_pk_fma_f32 v[56:57], v[94:95], v[56:57], 1.0 op_sel_hi:[1,1,0]
	s_nop 0
	v_pk_mul_f32 v[56:57], v[30:31], v[56:57]
	v_pk_mul_f32 v[30:31], v[30:31], v[50:51]
	v_pk_mul_f32 v[60:61], v[108:109], v[56:57]
	v_pk_mul_f32 v[50:51], v[30:31], v[30:31]
	v_fmac_f32_e32 v159, v90, v60
	v_max_f32_e64 v60, -v20, 0
	v_mul_f32_e64 v20, |v20|, s26
	v_exp_f32_e32 v20, v20
	v_fmac_f32_e32 v159, v91, v61
	v_add_f32_e32 v20, 1.0, v20
	s_nop 1
	v_log_f32_e32 v20, v20
	s_nop 0
	v_mul_f32_e32 v61, 0x3f317217, v20
	v_fma_f32 v61, v20, s34, -v61
	v_fmac_f32_e32 v61, 0x3377d1cf, v20
	v_fmac_f32_e32 v61, 0x3f317217, v20
	s_nop 1
	v_mov_b32_e32 v20, v61
	v_add_f32_e32 v20, v60, v20
	v_sub_f32_e32 v20, -0.5, v20
	v_mul_f32_e32 v20, 0x3fb8aa3b, v20
	v_exp_f32_e32 v20, v20
	v_and_b32_e32 v61, 0xffff0000, v58
	v_xor_b32_e32 v64, 0x80000000, v20
	v_add_f32_e32 v20, v21, v65
	v_max_f32_e64 v21, -v20, 0
	v_mul_f32_e64 v20, |v20|, s26
	v_exp_f32_e32 v20, v20
	s_nop 0
	v_add_f32_e32 v20, 1.0, v20
	s_nop 1
	v_log_f32_e32 v20, v20
	s_nop 0
	v_mul_f32_e32 v60, 0x3f317217, v20
	v_fma_f32 v60, v20, s34, -v60
	v_fmac_f32_e32 v60, 0x3377d1cf, v20
	v_fmac_f32_e32 v60, 0x3f317217, v20
	s_nop 1
	v_mov_b32_e32 v20, v60
	v_add_f32_e32 v20, v21, v20
	v_sub_f32_e32 v20, -0.5, v20
	v_mul_f32_e32 v20, 0x3fb8aa3b, v20
	v_exp_f32_e32 v20, v20
	v_and_b32_e32 v21, 0xffff0000, v62
	v_lshlrev_b32_e32 v60, 16, v58
	v_xor_b32_e32 v65, 0x80000000, v20
	v_lshlrev_b32_e32 v20, 16, v62
	v_pk_fma_f32 v[60:61], v[178:179], v[60:61], v[20:21] op_sel_hi:[0,1,1] neg_lo:[0,0,1] neg_hi:[0,0,1]
	v_pk_fma_f32 v[20:21], v[52:53], v[60:61], v[20:21]
	v_rcp_f32_e32 v17, v17
	v_max_f32_e64 v58, -v22, 0
	v_mul_f32_e64 v22, |v22|, s26
	v_exp_f32_e32 v22, v22
	v_rcp_f32_e32 v16, v16
	s_nop 0
	v_pk_add_f32 v[52:53], v[16:17], -1.0 op_sel_hi:[1,0]
	v_add_f32_e32 v22, 1.0, v22
	v_pk_fma_f32 v[52:53], v[76:77], v[52:53], 1.0 op_sel_hi:[1,1,0]
	s_nop 0
	v_log_f32_e32 v22, v22
	v_pk_mul_f32 v[60:61], v[20:21], v[52:53]
	v_pk_mul_f32 v[20:21], v[20:21], v[68:69]
	v_pk_mul_f32 v[76:77], v[104:105], v[60:61]
	v_mul_f32_e32 v62, 0x3f317217, v22
	v_fma_f32 v62, v22, s34, -v62
	v_fmac_f32_e32 v62, 0x3377d1cf, v22
	v_fmac_f32_e32 v62, 0x3f317217, v22
	v_fmac_f32_e32 v159, v72, v76
	v_fmac_f32_e32 v159, v73, v77
	v_mov_b32_e32 v22, v62
	v_add_f32_e32 v22, v58, v22
	v_sub_f32_e32 v22, -0.5, v22
	v_mul_f32_e32 v22, 0x3fb8aa3b, v22
	v_exp_f32_e32 v22, v22
	v_pk_mul_f32 v[52:53], v[20:21], v[20:21]
	v_xor_b32_e32 v68, 0x80000000, v22
	v_add_f32_e32 v22, v23, v67
	v_max_f32_e64 v23, -v22, 0
	v_mul_f32_e64 v22, |v22|, s26
	v_exp_f32_e32 v22, v22
	v_and_b32_e32 v67, 0xffff0000, v36
	v_lshlrev_b32_e32 v36, 16, v37
	v_and_b32_e32 v37, 0xffff0000, v37
	v_add_f32_e32 v22, 1.0, v22
	s_nop 1
	v_log_f32_e32 v22, v22
	s_nop 0
	v_mul_f32_e32 v58, 0x3f317217, v22
	v_fma_f32 v58, v22, s34, -v58
	v_fmac_f32_e32 v58, 0x3377d1cf, v22
	v_fmac_f32_e32 v58, 0x3f317217, v22
	s_nop 1
	v_mov_b32_e32 v22, v58
	v_add_f32_e32 v22, v23, v22
	v_sub_f32_e32 v22, -0.5, v22
	v_mul_f32_e32 v22, 0x3fb8aa3b, v22
	v_exp_f32_e32 v22, v22
	v_and_b32_e32 v23, 0xffff0000, v63
	v_lshlrev_b32_e32 v58, 16, v59
	v_and_b32_e32 v59, 0xffff0000, v59
	v_xor_b32_e32 v69, 0x80000000, v22
	v_lshlrev_b32_e32 v22, 16, v63
	v_pk_fma_f32 v[58:59], v[178:179], v[58:59], v[22:23] op_sel_hi:[0,1,1] neg_lo:[0,0,1] neg_hi:[0,0,1]
	v_pk_fma_f32 v[22:23], v[54:55], v[58:59], v[22:23]
	v_rcp_f32_e32 v19, v19
	v_rcp_f32_e32 v18, v18
	s_nop 0
	v_pk_add_f32 v[54:55], v[18:19], -1.0 op_sel_hi:[1,0]
	s_nop 0
	v_pk_fma_f32 v[54:55], v[78:79], v[54:55], 1.0 op_sel_hi:[1,1,0]
	s_nop 0
	v_pk_mul_f32 v[54:55], v[22:23], v[54:55]
	v_pk_mul_f32 v[22:23], v[22:23], v[70:71]
	v_pk_mul_f32 v[58:59], v[106:107], v[54:55]
	v_pk_mul_f32 v[62:63], v[22:23], v[22:23]
	v_fmac_f32_e32 v159, v74, v58
	v_fmac_f32_e32 v159, v75, v59
	v_lshlrev_b32_e32 v58, 16, v40
	v_and_b32_e32 v59, 0xffff0000, v40
	v_lshlrev_b32_e32 v40, 16, v41
	v_and_b32_e32 v41, 0xffff0000, v41
	v_pk_fma_f32 v[36:37], v[178:179], v[36:37], v[40:41] op_sel_hi:[0,1,1] neg_lo:[0,0,1] neg_hi:[0,0,1]
	v_pk_fma_f32 v[36:37], v[46:47], v[36:37], v[40:41]
	v_lshlrev_b32_e32 v40, 16, v42
	v_and_b32_e32 v41, 0xffff0000, v42
	v_lshlrev_b32_e32 v46, 16, v38
	v_and_b32_e32 v47, 0xffff0000, v38
	v_pk_fma_f32 v[46:47], v[178:179], v[46:47], v[40:41] op_sel_hi:[0,1,1] neg_lo:[0,0,1] neg_hi:[0,0,1]
	v_pk_fma_f32 v[40:41], v[32:33], v[46:47], v[40:41]
	v_lshlrev_b32_e32 v32, 16, v43
	v_and_b32_e32 v33, 0xffff0000, v43
	v_lshlrev_b32_e32 v38, 16, v39
	v_and_b32_e32 v39, 0xffff0000, v39
	v_pk_fma_f32 v[38:39], v[178:179], v[38:39], v[32:33] op_sel_hi:[0,1,1] neg_lo:[0,0,1] neg_hi:[0,0,1]
	v_pk_fma_f32 v[66:67], v[178:179], v[66:67], v[58:59] op_sel_hi:[0,1,1] neg_lo:[0,0,1] neg_hi:[0,0,1]
	v_pk_fma_f32 v[38:39], v[34:35], v[38:39], v[32:33]
	v_cvt_pk_bf16_f32 v32, v180, v181
	v_cvt_pk_bf16_f32 v33, v108, v109
	v_cvt_pk_bf16_f32 v34, v104, v105
	v_cvt_pk_bf16_f32 v35, v106, v107
	v_pk_fma_f32 v[44:45], v[44:45], v[66:67], v[58:59]
	ds_write_b128 v198, v[32:35] offset:1024
	ds_read_b128 v[246:249], v199 offset:1024
	v_lshl_add_u64 v[250:251], v[208:209], 0, v[202:203]
	s_waitcnt lgkmcnt(2)
	global_store_dwordx4 v[230:231], v[232:235], off
	s_nop 1
	v_cvt_pk_bf16_f32 v32, v84, v85
	v_cvt_pk_bf16_f32 v33, v56, v57
	v_cvt_pk_bf16_f32 v34, v60, v61
	v_cvt_pk_bf16_f32 v35, v54, v55
	ds_write_b128 v198, v[32:35]
	ds_read_b128 v[232:235], v199
	v_lshl_add_u64 v[230:231], v[208:209], 0, v[202:203]
	s_waitcnt lgkmcnt(2)
	global_store_dwordx4 v[250:251], v[246:249], off offset:64
	s_nop 1
	v_cvt_pk_bf16_f32 v32, v44, v45
	v_cvt_pk_bf16_f32 v33, v36, v37
	v_cvt_pk_bf16_f32 v34, v40, v41
	v_cvt_pk_bf16_f32 v35, v38, v39
	ds_write_b128 v198, v[32:35] offset:1024
	ds_read_b128 v[246:249], v199 offset:1024
	v_lshl_add_u64 v[250:251], v[208:209], 0, v[202:203]
	s_waitcnt lgkmcnt(2)
	global_store_dwordx4 v[230:231], v[232:235], off offset:576
	s_nop 1
	v_cvt_pk_bf16_f32 v32, v96, v97
	v_cvt_pk_bf16_f32 v33, v88, v89
	v_cvt_pk_bf16_f32 v34, v64, v65
	v_cvt_pk_bf16_f32 v35, v68, v69
	ds_write_b128 v198, v[32:35]
	ds_read_b128 v[232:235], v199
	v_lshl_add_u64 v[230:231], v[208:209], 0, v[202:203]
	s_waitcnt lgkmcnt(2)
	global_store_dwordx4 v[250:251], v[246:249], off offset:1088
	ds_write_b128 v198, v[0:3] offset:1024
	ds_read_b128 v[246:249], v199 offset:1024
	v_lshl_add_u64 v[250:251], v[212:213], 0, v[204:205]
	s_waitcnt lgkmcnt(2)
	global_store_dwordx4 v[230:231], v[232:235], off offset:2624
	s_nop 0
	v_pk_mul_f32 v[32:33], v[8:9], v[8:9]
	v_pk_mul_f32 v[2:3], v[210:211], v[14:15]
	v_pk_mul_f32 v[14:15], v[10:11], v[10:11]
	v_add_f32_e32 v32, v32, v33
	v_add_f32_e32 v14, v14, v32
	v_add_f32_e32 v14, v15, v14
	v_add_f32_e32 v12, v14, v12
	v_pk_mul_f32 v[4:5], v[2:3], v[2:3]
	v_add_f32_e32 v12, v13, v12
	v_add_f32_e32 v4, v4, v12
	v_pk_mul_f32 v[34:35], v[28:29], v[28:29]
	v_add_f32_e32 v4, v5, v4
	v_add_f32_e32 v4, v4, v34
	v_add_f32_e32 v4, v35, v4
	v_add_f32_e32 v4, v50, v4
	v_and_b32_e32 v1, 64, v243
	v_add_f32_e32 v4, v51, v4
	v_xor_b32_e32 v0, 16, v243
	v_add_u32_e32 v1, 64, v1
	v_add_f32_e32 v4, v4, v52
	v_cmp_lt_i32_e32 vcc, v0, v1
	v_add_f32_e32 v4, v53, v4
	v_add_f32_e32 v4, v62, v4
	v_cndmask_b32_e32 v0, v243, v0, vcc
	v_lshlrev_b32_e32 v36, 2, v0
	v_add_f32_e32 v4, v63, v4
	ds_bpermute_b32 v5, v36, v4
	v_xor_b32_e32 v0, 32, v243
	v_cmp_lt_i32_e32 vcc, v0, v1
	s_waitcnt lgkmcnt(0)
	v_add_f32_e32 v4, v4, v5
	v_cndmask_b32_e32 v0, v243, v0, vcc
	v_lshlrev_b32_e32 v37, 2, v0
	ds_bpermute_b32 v5, v37, v4
	ds_bpermute_b32 v0, v36, v159
	s_waitcnt lgkmcnt(0)
	v_add_f32_e32 v4, v4, v5
	v_cmp_gt_f32_e32 vcc, s36, v4
	v_mul_f32_e32 v5, 0x4f800000, v4
	v_add_f32_e32 v0, v159, v0
	v_cndmask_b32_e32 v4, v4, v5, vcc
	v_sqrt_f32_e32 v5, v4
	ds_bpermute_b32 v1, v37, v0
	v_add_u32_e32 v12, -1, v5
	v_fma_f32 v13, -v12, v5, v4
	v_cmp_ge_f32_e64 s[0:1], 0, v13
	v_add_u32_e32 v13, 1, v5
	s_nop 0
	v_cndmask_b32_e64 v12, v5, v12, s[0:1]
	v_fma_f32 v5, -v13, v5, v4
	v_cmp_lt_f32_e64 s[0:1], 0, v5
	s_nop 1
	v_cndmask_b32_e64 v5, v12, v13, s[0:1]
	v_mul_f32_e32 v12, 0x37800000, v5
	v_cndmask_b32_e32 v5, v5, v12, vcc
	v_cmp_class_f32_e32 vcc, v4, v237
	s_nop 1
	v_cndmask_b32_e32 v4, v5, v4, vcc
	v_max_f32_e32 v4, 0x2b8cbccc, v4
	v_rcp_f32_e32 v12, v4
	s_nop 0
	v_pk_mul_f32 v[4:5], v[8:9], v[12:13] op_sel_hi:[1,0]
	v_pk_mul_f32 v[10:11], v[10:11], v[12:13] op_sel_hi:[1,0]
	v_pk_mul_f32 v[6:7], v[6:7], v[12:13] op_sel_hi:[1,0]
	v_pk_mul_f32 v[34:35], v[2:3], v[12:13] op_sel_hi:[1,0]
	v_pk_mul_f32 v[8:9], v[116:117], v[4:5]
	v_pk_mul_f32 v[14:15], v[118:119], v[10:11]
	v_pk_mul_f32 v[32:33], v[188:189], v[6:7]
	v_pk_mul_f32 v[36:37], v[206:207], v[34:35]
	v_cvt_pk_bf16_f32 v2, v4, v5
	v_cvt_pk_bf16_f32 v3, v10, v11
	v_cvt_pk_bf16_f32 v4, v6, v7
	v_cvt_pk_bf16_f32 v5, v34, v35
	ds_write_b128 v198, v[2:5]
	ds_read_b128 v[232:235], v199
	v_lshl_add_u64 v[230:231], v[208:209], 0, v[202:203]
	s_waitcnt lgkmcnt(2)
	global_store_dwordx4 v[250:251], v[246:249], off offset:64
	v_pk_mul_f32 v[10:11], v[20:21], v[12:13] op_sel_hi:[1,0]
	s_nop 0
	v_cvt_pk_bf16_f32 v2, v8, v9
	v_cvt_pk_bf16_f32 v3, v14, v15
	v_cvt_pk_bf16_f32 v4, v32, v33
	v_cvt_pk_bf16_f32 v5, v36, v37
	ds_write_b128 v198, v[2:5] offset:1024
	ds_read_b128 v[246:249], v199 offset:1024
	v_lshl_add_u64 v[250:251], v[208:209], 0, v[202:203]
	s_waitcnt lgkmcnt(2)
	global_store_dwordx4 v[230:231], v[232:235], off offset:1536
	v_pk_mul_f32 v[14:15], v[16:17], v[10:11]
	s_nop 0
	v_pk_mul_f32 v[2:3], v[28:29], v[12:13] op_sel_hi:[1,0]
	v_pk_mul_f32 v[4:5], v[30:31], v[12:13] op_sel_hi:[1,0]
	v_pk_mul_f32 v[12:13], v[22:23], v[12:13] op_sel_hi:[1,0]
	v_pk_mul_f32 v[6:7], v[24:25], v[2:3]
	v_pk_mul_f32 v[8:9], v[26:27], v[4:5]
	v_pk_mul_f32 v[16:17], v[18:19], v[12:13]
	v_cvt_pk_bf16_f32 v2, v2, v3
	v_cvt_pk_bf16_f32 v3, v4, v5
	v_cvt_pk_bf16_f32 v4, v10, v11
	v_cvt_pk_bf16_f32 v5, v12, v13
	ds_write_b128 v198, v[2:5]
	ds_read_b128 v[232:235], v199
	v_lshl_add_u64 v[230:231], v[208:209], 0, v[202:203]
	s_waitcnt lgkmcnt(2)
	global_store_dwordx4 v[250:251], v[246:249], off offset:2048
	s_nop 1
	v_cvt_pk_bf16_f32 v2, v6, v7
	v_cvt_pk_bf16_f32 v3, v8, v9
	v_cvt_pk_bf16_f32 v4, v14, v15
	v_cvt_pk_bf16_f32 v5, v16, v17
	ds_write_b128 v198, v[2:5] offset:1024
	ds_read_b128 v[246:249], v199 offset:1024
	v_lshl_add_u64 v[250:251], v[208:209], 0, v[202:203]
	s_waitcnt lgkmcnt(2)
	global_store_dwordx4 v[230:231], v[232:235], off offset:1600
	s_waitcnt lgkmcnt(0)
	global_store_dwordx4 v[250:251], v[246:249], off offset:2112
	s_and_saveexec_b64 s[0:1], s[8:9]
	s_cbranch_execz .LBB0_341
	v_lshl_add_u64 v[2:3], v[176:177], 4, s[16:17]
	s_waitcnt lgkmcnt(0)
	v_add_f32_e32 v0, v0, v1
	global_store_dword v[2:3], v0, off
	s_branch .LBB0_341

.LBB0_347:
	s_and_b32 s0, s3, -16
	s_addk_i32 s0, 0x4000
	v_or_b32_e32 v206, s0, v193
	s_waitcnt lgkmcnt(0)
	v_mov_b64_e32 v[0:1], s[10:11]
	v_mad_i64_i32 v[0:1], s[0:1], v206, s86, v[0:1]
	s_mov_b64 s[0:1], 0x2040c00
	s_nop 0
	v_lshl_add_u64 v[208:209], v[0:1], 0, s[0:1]
	v_add_u32_e32 v0, 0xffffc000, v206
	v_ashrrev_i32_e32 v1, 31, v0
	v_lshl_add_u64 v[0:1], v[0:1], 0, s[42:43]
	v_mov_b64_e32 v[2:3], s[46:47]
	s_movk_i32 s4, 0xe00
	v_mad_u64_u32 v[210:211], s[0:1], v0, s4, v[2:3]
	v_mad_i32_i24 v211, v1, s4, v211
	v_lshl_add_u64 v[0:1], v[208:209], 0, v[194:195]
	global_load_dwordx4 v[132:135], v[0:1], off
	v_mov_b32_e32 v175, v195
	v_lshl_add_u64 v[0:1], v[210:211], 0, v[174:175]
	global_load_dwordx4 v[128:131], v[0:1], off offset:3072
	global_load_dwordx4 v[212:215], v[0:1], off offset:3088
	global_load_dwordx4 v[84:87], v[136:137], off offset:3072
	global_load_dwordx4 v[216:219], v[136:137], off offset:3088
	v_mov_b32_e32 v177, v195
	v_lshl_add_u64 v[2:3], v[208:209], 0, v[176:177]
	v_mov_b32_e32 v179, v195
	global_load_dwordx4 v[108:111], v[2:3], off
	global_load_dwordx4 v[88:91], v[0:1], off offset:3216
	global_load_dwordx4 v[120:123], v[0:1], off offset:3200
	global_load_dwordx4 v[116:119], v[136:137], off offset:3216
	global_load_dwordx4 v[124:127], v[136:137], off offset:3200
	v_lshl_add_u64 v[2:3], v[208:209], 0, v[178:179]
	v_mov_b32_e32 v181, v195
	global_load_dwordx4 v[92:95], v[2:3], off
	global_load_dwordx4 v[96:99], v[0:1], off offset:3328
	global_load_dwordx4 v[104:107], v[0:1], off offset:3344
	global_load_dwordx4 v[100:103], v[136:137], off offset:3328
	global_load_dwordx4 v[112:115], v[136:137], off offset:3344
	v_lshl_add_u64 v[2:3], v[208:209], 0, v[180:181]
	global_load_dwordx4 v[64:67], v[2:3], off
	global_load_dwordx4 v[68:71], v[0:1], off offset:3456
	global_load_dwordx4 v[76:79], v[0:1], off offset:3472
	global_load_dwordx4 v[72:75], v[136:137], off offset:3456
	global_load_dwordx4 v[80:83], v[136:137], off offset:3472
	global_load_dwordx4 v[60:63], v[140:141], off
	global_load_dwordx4 v[56:59], v[140:141], off offset:64
	global_load_dwordx4 v[52:55], v[140:141], off offset:128
	global_load_dwordx4 v[28:31], v[140:141], off offset:192
	global_load_dwordx4 v[24:27], v[140:141], off offset:1024
	global_load_dwordx4 v[0:3], v[140:141], off offset:1088
	global_load_dwordx4 v[4:7], v[140:141], off offset:1152
	global_load_dwordx4 v[8:11], v[140:141], off offset:1216
	global_load_dwordx4 v[12:15], v[142:143], off
	global_load_dwordx4 v[16:19], v[144:145], off
	global_load_dwordx4 v[20:23], v[146:147], off
	global_load_dwordx4 v[32:35], v[148:149], off
	global_load_dwordx4 v[36:39], v[150:151], off
	global_load_dwordx4 v[40:43], v[152:153], off
	global_load_dwordx4 v[44:47], v[154:155], off
	global_load_dwordx4 v[48:51], v[156:157], off
	v_mov_b32_e32 v183, v195
	v_mov_b32_e32 v185, v195
	s_mov_b32 s4, 0x800000
	s_mov_b32 s5, 0x3f317217
	s_mov_b32 s6, 0x7f800000
	v_ashrrev_i32_e32 v207, 31, v206
	v_mov_b32_e32 v187, v195
	v_mov_b32_e32 v189, v195
	v_mov_b32_e32 v191, v195
	s_waitcnt vmcnt(0) lgkmcnt(0)
	v_and_b32_e32 v177, 0xffff0000, v132
	v_lshlrev_b32_e32 v179, 16, v133
	v_sub_f32_e32 v129, v129, v177
	v_and_b32_e32 v181, 0xffff0000, v133
	v_fmac_f32_e32 v177, v85, v129
	v_sub_f32_e32 v85, v130, v179
	v_lshlrev_b32_e32 v175, 16, v134
	v_fmac_f32_e32 v179, v86, v85
	v_sub_f32_e32 v85, v131, v181
	v_and_b32_e32 v139, 0xffff0000, v134
	v_fmac_f32_e32 v181, v87, v85
	v_sub_f32_e32 v85, v212, v175
	v_lshlrev_b32_e32 v134, 16, v135
	v_fmac_f32_e32 v175, v85, v216
	v_sub_f32_e32 v85, v213, v139
	v_and_b32_e32 v133, 0xffff0000, v135
	v_fmac_f32_e32 v139, v85, v217
	v_sub_f32_e32 v85, v214, v134
	v_fmac_f32_e32 v134, v85, v218
	v_sub_f32_e32 v85, v215, v133
	v_fmac_f32_e32 v133, v85, v219
	v_lshlrev_b32_e32 v85, 16, v132
	v_sub_f32_e32 v86, v128, v85
	v_fmac_f32_e32 v85, v84, v86
	v_add_f32_e32 v84, v85, v85
	v_add_f32_e32 v85, v177, v177
	v_mul_f32_e32 v84, 0x3fb8aa3b, v84
	v_mul_f32_e32 v85, 0x3fb8aa3b, v85
	v_exp_f32_e32 v84, v84
	v_exp_f32_e32 v85, v85
	v_lshlrev_b64 v[216:217], 9, v[206:207]
	v_lshl_add_u64 v[216:217], v[172:173], 0, v[216:217]
	v_pk_add_f32 v[84:85], v[84:85], 1.0 op_sel_hi:[1,0]
	s_nop 0
	v_rcp_f32_e32 v85, v85
	s_nop 0
	v_mul_f32_e32 v85, 2.0, v85
	v_rcp_f32_e32 v84, v84
	s_nop 0
	v_mul_f32_e32 v84, 2.0, v84
	v_add_f32_e32 v86, v179, v179
	v_add_f32_e32 v87, v181, v181
	v_mul_f32_e32 v86, 0x3fb8aa3b, v86
	v_mul_f32_e32 v87, 0x3fb8aa3b, v87
	v_exp_f32_e32 v86, v86
	v_exp_f32_e32 v87, v87
	v_pk_add_f32 v[84:85], v[84:85], 1.0 op_sel_hi:[1,0] neg_lo:[1,0] neg_hi:[1,0]
	v_pk_add_f32 v[86:87], v[86:87], 1.0 op_sel_hi:[1,0]
	s_nop 0
	v_cvt_pk_bf16_f32 v84, v84, v85
	v_rcp_f32_e32 v87, v87
	s_nop 0
	v_mul_f32_e32 v87, 2.0, v87
	v_rcp_f32_e32 v86, v86
	s_nop 0
	v_mul_f32_e32 v86, 2.0, v86
	v_add_f32_e32 v128, v175, v175
	v_add_f32_e32 v129, v139, v139
	v_mul_f32_e32 v128, 0x3fb8aa3b, v128
	v_mul_f32_e32 v129, 0x3fb8aa3b, v129
	v_exp_f32_e32 v128, v128
	v_exp_f32_e32 v129, v129
	v_pk_add_f32 v[86:87], v[86:87], 1.0 op_sel_hi:[1,0] neg_lo:[1,0] neg_hi:[1,0]
	v_pk_add_f32 v[128:129], v[128:129], 1.0 op_sel_hi:[1,0]
	s_nop 0
	v_cvt_pk_bf16_f32 v85, v86, v87
	v_rcp_f32_e32 v129, v129
	s_nop 0
	v_mul_f32_e32 v129, 2.0, v129
	v_rcp_f32_e32 v128, v128
	s_nop 0
	v_mul_f32_e32 v128, 2.0, v128
	v_add_f32_e32 v130, v134, v134
	v_add_f32_e32 v131, v133, v133
	v_pk_add_f32 v[128:129], v[128:129], 1.0 op_sel_hi:[1,0] neg_lo:[1,0] neg_hi:[1,0]
	v_mul_f32_e32 v130, 0x3fb8aa3b, v130
	v_mul_f32_e32 v131, 0x3fb8aa3b, v131
	v_exp_f32_e32 v130, v130
	v_exp_f32_e32 v131, v131
	v_cvt_pk_bf16_f32 v86, v128, v129
	v_lshlrev_b32_e32 v128, 16, v108
	v_and_b32_e32 v129, 0xffff0000, v108
	v_lshlrev_b32_e32 v108, 16, v109
	v_and_b32_e32 v109, 0xffff0000, v109
	v_pk_add_f32 v[122:123], v[122:123], v[108:109] neg_lo:[0,1] neg_hi:[0,1]
	v_pk_add_f32 v[130:131], v[130:131], 1.0 op_sel_hi:[1,0]
	v_pk_fma_f32 v[108:109], v[126:127], v[122:123], v[108:109]
	v_lshlrev_b32_e32 v122, 16, v110
	v_and_b32_e32 v123, 0xffff0000, v110
	v_pk_add_f32 v[88:89], v[88:89], v[122:123] neg_lo:[0,1] neg_hi:[0,1]
	s_nop 0
	v_pk_fma_f32 v[116:117], v[88:89], v[116:117], v[122:123]
	v_lshlrev_b32_e32 v88, 16, v111
	v_and_b32_e32 v89, 0xffff0000, v111
	v_pk_add_f32 v[90:91], v[90:91], v[88:89] neg_lo:[0,1] neg_hi:[0,1]
	s_nop 0
	v_pk_fma_f32 v[110:111], v[90:91], v[118:119], v[88:89]
	v_cvt_pk_bf16_f32 v89, v108, v109
	v_and_b32_e32 v108, 0xffff0000, v92
	v_cvt_pk_bf16_f32 v91, v110, v111
	v_lshlrev_b32_e32 v109, 16, v93
	v_and_b32_e32 v110, 0xffff0000, v93
	v_sub_f32_e32 v93, v97, v108
	v_fmac_f32_e32 v108, v101, v93
	v_sub_f32_e32 v93, v98, v109
	v_lshlrev_b32_e32 v111, 16, v94
	v_fmac_f32_e32 v109, v102, v93
	v_sub_f32_e32 v93, v99, v110
	v_and_b32_e32 v94, 0xffff0000, v94
	v_fmac_f32_e32 v110, v103, v93
	v_sub_f32_e32 v93, v104, v111
	v_cvt_pk_bf16_f32 v90, v116, v117
	v_lshlrev_b32_e32 v116, 16, v95
	v_fmac_f32_e32 v111, v93, v112
	v_sub_f32_e32 v93, v105, v94
	v_and_b32_e32 v95, 0xffff0000, v95
	v_fmac_f32_e32 v94, v93, v113
	v_sub_f32_e32 v93, v106, v116
	v_fmac_f32_e32 v116, v93, v114
	v_sub_f32_e32 v93, v107, v95
	v_lshlrev_b32_e32 v92, 16, v92
	v_fmac_f32_e32 v95, v93, v115
	v_sub_f32_e32 v93, v96, v92
	v_fmac_f32_e32 v92, v100, v93
	v_mul_f32_e32 v92, 0xbfb8aa3b, v92
	v_mul_f32_e32 v93, 0xbfb8aa3b, v108
	v_rcp_f32_e32 v131, v131
	s_nop 0
	v_mul_f32_e32 v131, 2.0, v131
	v_exp_f32_e32 v92, v92
	v_exp_f32_e32 v93, v93
	v_pk_add_f32 v[120:121], v[120:121], v[128:129] neg_lo:[0,1] neg_hi:[0,1]
	v_pk_add_f32 v[92:93], v[92:93], 1.0 op_sel_hi:[1,0]
	s_nop 0
	v_rcp_f32_e32 v96, v93
	v_rcp_f32_e32 v130, v130
	s_nop 0
	v_mul_f32_e32 v130, 2.0, v130
	v_pk_add_f32 v[130:131], v[130:131], 1.0 op_sel_hi:[1,0] neg_lo:[1,0] neg_hi:[1,0]
	v_pk_fma_f32 v[120:121], v[124:125], v[120:121], v[128:129]
	v_rcp_f32_e32 v97, v92
	v_mul_f32_e32 v92, 0xbfb8aa3b, v109
	v_mul_f32_e32 v93, 0xbfb8aa3b, v110
	v_exp_f32_e32 v92, v92
	v_exp_f32_e32 v93, v93
	v_cvt_pk_bf16_f32 v87, v130, v131
	v_cvt_pk_bf16_f32 v88, v120, v121
	v_pk_add_f32 v[92:93], v[92:93], 1.0 op_sel_hi:[1,0]
	s_nop 0
	v_rcp_f32_e32 v98, v93
	v_rcp_f32_e32 v99, v92
	v_mul_f32_e32 v92, 0xbfb8aa3b, v111
	v_mul_f32_e32 v93, 0xbfb8aa3b, v94
	v_exp_f32_e32 v92, v92
	v_exp_f32_e32 v93, v93
	s_nop 0
	v_pk_add_f32 v[92:93], v[92:93], 1.0 op_sel_hi:[1,0]
	s_nop 0
	v_rcp_f32_e32 v94, v93
	v_rcp_f32_e32 v100, v92
	v_mul_f32_e32 v92, 0xbfb8aa3b, v116
	v_mul_f32_e32 v93, 0xbfb8aa3b, v95
	v_exp_f32_e32 v92, v92
	v_exp_f32_e32 v93, v93
	v_cvt_pk_bf16_f32 v94, v100, v94
	v_lshlrev_b32_e32 v100, 16, v67
	v_and_b32_e32 v67, 0xffff0000, v67
	v_pk_add_f32 v[92:93], v[92:93], 1.0 op_sel_hi:[1,0]
	s_nop 0
	v_rcp_f32_e32 v95, v93
	v_rcp_f32_e32 v101, v92
	v_cvt_pk_bf16_f32 v92, v97, v96
	v_and_b32_e32 v96, 0xffff0000, v64
	v_cvt_pk_bf16_f32 v93, v99, v98
	v_lshlrev_b32_e32 v97, 16, v65
	v_and_b32_e32 v98, 0xffff0000, v65
	v_sub_f32_e32 v65, v69, v96
	v_fmac_f32_e32 v96, v73, v65
	v_sub_f32_e32 v65, v70, v97
	v_lshlrev_b32_e32 v99, 16, v66
	v_fmac_f32_e32 v97, v74, v65
	v_sub_f32_e32 v65, v71, v98
	v_and_b32_e32 v66, 0xffff0000, v66
	v_fmac_f32_e32 v98, v75, v65
	v_sub_f32_e32 v65, v76, v99
	v_fmac_f32_e32 v99, v65, v80
	v_sub_f32_e32 v65, v77, v66
	v_fmac_f32_e32 v66, v65, v81
	v_sub_f32_e32 v65, v78, v100
	v_fmac_f32_e32 v100, v65, v82
	v_sub_f32_e32 v65, v79, v67
	v_lshlrev_b32_e32 v64, 16, v64
	v_fmac_f32_e32 v67, v65, v83
	v_sub_f32_e32 v65, v68, v64
	v_fmac_f32_e32 v64, v72, v65
	v_mul_f32_e32 v64, 0xbfb8aa3b, v64
	v_mul_f32_e32 v65, 0xbfb8aa3b, v96
	v_exp_f32_e32 v64, v64
	v_exp_f32_e32 v65, v65
	v_cvt_pk_bf16_f32 v95, v101, v95
	v_pk_add_f32 v[64:65], v[64:65], 1.0 op_sel_hi:[1,0]
	s_nop 0
	v_mfma_f32_16x16x32_bf16 v[52:55], v[52:55], v[92:95], 0
	v_rcp_f32_e32 v68, v65
	v_rcp_f32_e32 v69, v64
	v_mul_f32_e32 v64, 0xbfb8aa3b, v97
	v_mul_f32_e32 v65, 0xbfb8aa3b, v98
	v_exp_f32_e32 v64, v64
	v_exp_f32_e32 v65, v65
	v_cvt_pk_bf16_f32 v68, v69, v68
	v_pk_add_f32 v[64:65], v[64:65], 1.0 op_sel_hi:[1,0]
	s_nop 0
	v_rcp_f32_e32 v70, v65
	v_rcp_f32_e32 v71, v64
	v_mul_f32_e32 v64, 0xbfb8aa3b, v99
	v_mul_f32_e32 v65, 0xbfb8aa3b, v66
	v_exp_f32_e32 v64, v64
	v_exp_f32_e32 v65, v65
	v_cvt_pk_bf16_f32 v69, v71, v70
	v_mfma_f32_16x16x32_bf16 v[96:99], v[56:59], v[88:91], 0
	v_add_f32_e64 v64, v64, 1.0
	v_add_f32_e64 v65, v65, 1.0
	v_rcp_f32_e32 v66, v65
	v_rcp_f32_e32 v72, v64
	v_mul_f32_e32 v64, 0xbfb8aa3b, v100
	v_mul_f32_e32 v65, 0xbfb8aa3b, v67
	v_exp_f32_e32 v64, v64
	v_exp_f32_e32 v65, v65
	v_mfma_f32_16x16x32_bf16 v[100:103], v[60:63], v[84:87], 0
	v_cvt_pk_bf16_f32 v70, v72, v66
	v_pk_add_f32 v[64:65], v[64:65], 1.0 op_sel_hi:[1,0]
	s_nop 0
	v_mfma_f32_16x16x32_bf16 v[60:63], v[0:3], v[88:91], 0
	v_rcp_f32_e32 v65, v65
	v_mfma_f32_16x16x32_bf16 v[0:3], v[4:7], v[92:95], 0
	v_rcp_f32_e32 v64, v64
	s_nop 0
	v_cvt_pk_bf16_f32 v71, v64, v65
	v_mfma_f32_16x16x32_bf16 v[4:7], v[44:47], v[92:95], 0
	s_nop 0
	v_mfma_f32_16x16x32_bf16 v[56:59], v[8:11], v[68:71], v[0:3]
	v_lshlrev_b32_e32 v8, 1, v138
	v_mov_b32_e32 v9, v195
	v_lshl_add_u64 v[8:9], v[208:209], 0, v[8:9]
	global_load_dwordx4 v[128:131], v[8:9], off
	v_lshlrev_b32_e32 v8, 2, v138
	v_mov_b32_e32 v9, v195
	v_lshl_add_u64 v[218:219], v[210:211], 0, v[8:9]
	v_mfma_f32_16x16x32_bf16 v[0:3], v[20:23], v[92:95], 0
	global_load_dwordx4 v[132:135], v[218:219], off offset:16
	global_load_dwordx4 v[212:215], v[218:219], off
	global_load_dwordx4 v[222:225], v[158:159], off offset:16
	global_load_dwordx4 v[226:229], v[158:159], off
	v_lshl_add_u64 v[8:9], v[208:209], 0, v[182:183]
	s_waitcnt vmcnt(0) lgkmcnt(0)
	v_lshlrev_b32_e32 v210, 16, v128
	v_mfma_f32_16x16x32_bf16 v[52:55], v[28:31], v[68:71], v[52:55]
	v_and_b32_e32 v211, 0xffff0000, v128
	v_pk_add_f32 v[212:213], v[212:213], v[210:211] neg_lo:[0,1] neg_hi:[0,1]
	v_lshlrev_b32_e32 v128, 16, v129
	v_mfma_f32_16x16x32_bf16 v[0:3], v[32:35], v[68:71], v[0:3]
	v_and_b32_e32 v129, 0xffff0000, v129
	v_pk_fma_f32 v[212:213], v[212:213], v[226:227], v[210:211]
	v_pk_add_f32 v[210:211], v[214:215], v[128:129] neg_lo:[0,1] neg_hi:[0,1]
	v_mfma_f32_16x16x32_bf16 v[4:7], v[48:51], v[68:71], v[4:7]
	global_load_dwordx4 v[68:71], v[8:9], off
	global_load_dwordx4 v[72:75], v[218:219], off offset:1040
	global_load_dwordx4 v[104:107], v[218:219], off offset:1024
	global_load_dwordx4 v[76:79], v[158:159], off offset:1040
	global_load_dwordx4 v[108:111], v[158:159], off offset:1024
	v_lshl_add_u64 v[8:9], v[208:209], 0, v[184:185]
	v_pk_fma_f32 v[220:221], v[210:211], v[228:229], v[128:129]
	v_mfma_f32_16x16x32_bf16 v[64:67], v[24:27], v[84:87], 0
	v_lshlrev_b32_e32 v128, 16, v130
	v_and_b32_e32 v129, 0xffff0000, v130
	v_pk_add_f32 v[132:133], v[132:133], v[128:129] neg_lo:[0,1] neg_hi:[0,1]
	v_mfma_f32_16x16x32_bf16 v[28:31], v[12:15], v[84:87], 0
	v_fma_f32 v222, v132, v222, v128
	v_fma_f32 v223, v133, v223, v129
	v_lshlrev_b32_e32 v128, 16, v131
	v_and_b32_e32 v129, 0xffff0000, v131
	v_mfma_f32_16x16x32_bf16 v[24:27], v[16:19], v[88:91], 0
	v_add_f32_e64 v130, v134, -v128
	v_add_f32_e64 v131, v135, -v129
	v_cvt_pk_bf16_f32 v0, v0, v1
	v_pk_fma_f32 v[224:225], v[130:131], v[224:225], v[128:129]
	v_mfma_f32_16x16x32_bf16 v[20:23], v[36:39], v[84:87], 0
	v_cvt_pk_bf16_f32 v1, v2, v3
	v_cvt_pk_bf16_f32 v2, v4, v5
	v_cvt_pk_bf16_f32 v3, v6, v7
	v_mfma_f32_16x16x32_bf16 v[16:19], v[40:43], v[88:91], 0
	global_load_dwordx4 v[40:43], v[8:9], off
	global_load_dwordx4 v[36:39], v[218:219], off offset:2064
	global_load_dwordx4 v[48:51], v[218:219], off offset:2048
	global_load_dwordx4 v[32:35], v[158:159], off offset:2064
	global_load_dwordx4 v[44:47], v[158:159], off offset:2048
	global_load_dwordx4 v[80:83], v[160:161], off offset:16
	global_load_dwordx4 v[124:127], v[160:161], off
	global_load_dwordx4 v[92:95], v[162:163], off offset:16
	global_load_dwordx4 v[120:123], v[162:163], off
	global_load_dwordx4 v[8:11], v[164:165], off
	global_load_dwordx4 v[12:15], v[164:165], off offset:16
	global_load_dwordx4 v[88:91], v[166:167], off offset:16
	global_load_dwordx4 v[116:119], v[166:167], off
	global_load_dwordx4 v[84:87], v[168:169], off offset:16
	global_load_dwordx4 v[112:115], v[168:169], off
	s_waitcnt vmcnt(0)
	v_add_f32_e32 v64, v64, v80
	v_add_f32_e32 v100, v100, v124
	v_max_f32_e64 v124, -v100, 0
	v_mul_f32_e64 v100, |v100|, s21
	v_exp_f32_e32 v100, v100
	v_add_f32_e32 v101, v101, v125
	v_add_f32_e32 v96, v96, v120
	v_max_f32_e64 v120, -v101, 0
	v_add_f32_e32 v100, 1.0, v100
	v_mul_f32_e64 v101, |v101|, s21
	v_exp_f32_e32 v101, v101
	v_log_f32_e32 v100, v100
	v_add_f32_e32 v101, 1.0, v101
	v_add_f32_e32 v97, v97, v121
	v_mul_f32_e32 v96, 0xbfb8aa3b, v96
	v_mul_f32_e32 v128, 0x3f317217, v100
	v_fma_f32 v128, v100, s5, -v128
	v_fmac_f32_e32 v128, 0x3377d1cf, v100
	v_fmac_f32_e32 v128, 0x3f317217, v100
	v_mul_f32_e32 v97, 0xbfb8aa3b, v97
	v_exp_f32_e32 v96, v96
	v_mov_b32_e32 v100, v128
	v_add_f32_e32 v100, v124, v100
	v_exp_f32_e32 v97, v97
	v_log_f32_e32 v101, v101
	s_waitcnt lgkmcnt(0)
	v_and_b32_e32 v121, 0xffff0000, v68
	v_pk_add_f32 v[96:97], v[96:97], 1.0 op_sel_hi:[1,0]
	v_max_f32_e64 v80, -v64, 0
	v_mul_f32_e32 v124, 0x3f317217, v101
	v_fma_f32 v124, v101, s5, -v124
	v_fmac_f32_e32 v124, 0x3377d1cf, v101
	v_fmac_f32_e32 v124, 0x3f317217, v101
	v_mul_f32_e64 v64, |v64|, s21
	v_exp_f32_e32 v64, v64
	v_mov_b32_e32 v101, v124
	v_add_f32_e32 v101, v120, v101
	v_lshlrev_b32_e32 v120, 16, v68
	v_pk_add_f32 v[104:105], v[104:105], v[120:121] neg_lo:[0,1] neg_hi:[0,1]
	s_nop 0
	v_pk_fma_f32 v[128:129], v[108:109], v[104:105], v[120:121]
	v_add_f32_e32 v64, 1.0, v64
	v_add_f32_e32 v65, v65, v81
	v_add_f32_e32 v60, v60, v92
	v_rcp_f32_e32 v125, v97
	v_add_f32_e32 v61, v61, v93
	v_mul_f32_e32 v60, 0xbfb8aa3b, v60
	v_mul_f32_e32 v61, 0xbfb8aa3b, v61
	v_rcp_f32_e32 v124, v96
	v_add_f32_e32 v68, v102, v126
	v_max_f32_e64 v102, -v68, 0
	v_mul_f32_e64 v68, |v68|, s21
	v_exp_f32_e32 v68, v68
	v_pk_add_f32 v[96:97], v[124:125], -1.0 op_sel_hi:[1,0]
	v_exp_f32_e32 v60, v60
	v_pk_fma_f32 v[96:97], v[116:117], v[96:97], 1.0 op_sel_hi:[1,1,0]
	v_add_f32_e32 v68, 1.0, v68
	v_pk_mul_f32 v[96:97], v[128:129], v[96:97]
	s_nop 0
	v_pk_mul_f32 v[104:105], v[212:213], v[96:97]
	v_exp_f32_e32 v61, v61
	v_fma_f32 v139, v112, v104, 0
	v_log_f32_e32 v68, v68
	v_fmac_f32_e32 v139, v113, v105
	v_pk_add_f32 v[60:61], v[60:61], 1.0 op_sel_hi:[1,0]
	v_add_f32_e32 v66, v66, v82
	v_mul_f32_e32 v104, 0x3f317217, v68
	v_fma_f32 v104, v68, s5, -v104
	v_fmac_f32_e32 v104, 0x3377d1cf, v68
	v_fmac_f32_e32 v104, 0x3f317217, v68
	v_add_f32_e32 v62, v62, v94
	v_add_f32_e32 v63, v63, v95
	v_mov_b32_e32 v68, v104
	v_add_f32_e32 v68, v102, v68
	v_sub_f32_e32 v68, -0.5, v68
	v_mul_f32_e32 v68, 0x3fb8aa3b, v68
	v_exp_f32_e32 v68, v68
	v_mul_f32_e32 v62, 0xbfb8aa3b, v62
	v_mul_f32_e32 v63, 0xbfb8aa3b, v63
	v_exp_f32_e32 v62, v62
	v_xor_b32_e32 v102, 0x80000000, v68
	v_add_f32_e32 v68, v98, v122
	v_mul_f32_e32 v68, 0xbfb8aa3b, v68
	v_exp_f32_e32 v104, v68
	v_add_f32_e32 v68, v103, v127
	v_max_f32_e64 v98, -v68, 0
	v_mul_f32_e64 v68, |v68|, s21
	v_exp_f32_e32 v68, v68
	v_exp_f32_e32 v63, v63
	v_sub_f32_e32 v100, -0.5, v100
	v_sub_f32_e32 v101, -0.5, v101
	v_add_f32_e32 v68, 1.0, v68
	v_pk_add_f32 v[62:63], v[62:63], 1.0 op_sel_hi:[1,0]
	v_mul_f32_e32 v100, 0x3fb8aa3b, v100
	v_log_f32_e32 v68, v68
	v_mul_f32_e32 v101, 0x3fb8aa3b, v101
	v_exp_f32_e32 v100, v100
	v_exp_f32_e32 v101, v101
	v_mul_f32_e32 v103, 0x3f317217, v68
	v_fma_f32 v103, v68, s5, -v103
	v_fmac_f32_e32 v103, 0x3377d1cf, v68
	v_fmac_f32_e32 v103, 0x3f317217, v68
	v_xor_b32_e32 v100, 0x80000000, v100
	v_xor_b32_e32 v101, 0x80000000, v101
	v_mov_b32_e32 v68, v103
	v_add_f32_e32 v68, v98, v68
	v_sub_f32_e32 v68, -0.5, v68
	v_mul_f32_e32 v68, 0x3fb8aa3b, v68
	v_exp_f32_e32 v68, v68
	v_pk_mul_f32 v[8:9], v[128:129], v[8:9]
	v_xor_b32_e32 v98, 0x80000000, v68
	v_add_f32_e32 v68, v99, v123
	v_mul_f32_e32 v68, 0xbfb8aa3b, v68
	v_exp_f32_e32 v105, v68
	v_lshlrev_b32_e32 v68, 16, v69
	v_and_b32_e32 v69, 0xffff0000, v69
	v_pk_add_f32 v[106:107], v[106:107], v[68:69] neg_lo:[0,1] neg_hi:[0,1]
	s_nop 0
	v_pk_fma_f32 v[130:131], v[110:111], v[106:107], v[68:69]
	v_pk_add_f32 v[68:69], v[104:105], 1.0 op_sel_hi:[1,0]
	v_pk_mul_f32 v[10:11], v[130:131], v[10:11]
	v_rcp_f32_e32 v127, v69
	v_rcp_f32_e32 v126, v68
	s_nop 0
	v_pk_add_f32 v[68:69], v[126:127], -1.0 op_sel_hi:[1,0]
	v_log_f32_e32 v64, v64
	v_pk_fma_f32 v[68:69], v[118:119], v[68:69], 1.0 op_sel_hi:[1,1,0]
	v_mul_f32_e32 v99, 0x3f317217, v64
	v_fma_f32 v99, v64, s5, -v99
	v_fmac_f32_e32 v99, 0x3377d1cf, v64
	v_fmac_f32_e32 v99, 0x3f317217, v64
	v_pk_mul_f32 v[68:69], v[130:131], v[68:69]
	s_nop 0
	v_mov_b32_e32 v64, v99
	v_add_f32_e32 v64, v80, v64
	v_max_f32_e64 v80, -v65, 0
	v_mul_f32_e64 v65, |v65|, s21
	v_exp_f32_e32 v65, v65
	v_pk_mul_f32 v[104:105], v[220:221], v[68:69]
	v_sub_f32_e32 v64, -0.5, v64
	v_fmac_f32_e32 v139, v114, v104
	v_add_f32_e32 v65, 1.0, v65
	v_fmac_f32_e32 v139, v115, v105
	v_mul_f32_e32 v64, 0x3fb8aa3b, v64
	v_log_f32_e32 v65, v65
	v_exp_f32_e32 v64, v64
	v_mul_f32_e32 v81, 0x3f317217, v65
	v_fma_f32 v81, v65, s5, -v81
	v_fmac_f32_e32 v81, 0x3377d1cf, v65
	v_fmac_f32_e32 v81, 0x3f317217, v65
	v_xor_b32_e32 v64, 0x80000000, v64
	s_nop 0
	v_mov_b32_e32 v65, v81
	v_add_f32_e32 v65, v80, v65
	v_lshlrev_b32_e32 v80, 16, v70
	v_and_b32_e32 v81, 0xffff0000, v70
	v_pk_add_f32 v[72:73], v[72:73], v[80:81] neg_lo:[0,1] neg_hi:[0,1]
	s_nop 0
	v_pk_fma_f32 v[134:135], v[72:73], v[76:77], v[80:81]
	v_sub_f32_e32 v65, -0.5, v65
	v_mul_f32_e32 v65, 0x3fb8aa3b, v65
	v_exp_f32_e32 v65, v65
	v_rcp_f32_e32 v133, v61
	v_xor_b32_e32 v65, 0x80000000, v65
	v_pk_mul_f32 v[6:7], v[134:135], v[12:13]
	v_max_f32_e64 v70, -v66, 0
	v_mul_f32_e64 v66, |v66|, s21
	v_exp_f32_e32 v66, v66
	v_rcp_f32_e32 v132, v60
	s_nop 0
	v_pk_add_f32 v[60:61], v[132:133], -1.0 op_sel_hi:[1,0]
	v_pk_mul_f32 v[12:13], v[6:7], v[6:7]
	v_pk_fma_f32 v[60:61], v[88:89], v[60:61], 1.0 op_sel_hi:[1,1,0]
	v_add_f32_e32 v66, 1.0, v66
	v_pk_mul_f32 v[60:61], v[134:135], v[60:61]
	s_nop 0
	v_pk_mul_f32 v[72:73], v[222:223], v[60:61]
	s_nop 0
	v_fmac_f32_e32 v139, v84, v72
	v_log_f32_e32 v66, v66
	v_fmac_f32_e32 v139, v85, v73
	v_mul_f32_e32 v72, 0x3f317217, v66
	v_fma_f32 v72, v66, s5, -v72
	v_fmac_f32_e32 v72, 0x3377d1cf, v66
	v_fmac_f32_e32 v72, 0x3f317217, v66
	s_nop 1
	v_mov_b32_e32 v66, v72
	v_add_f32_e32 v66, v70, v66
	v_sub_f32_e32 v66, -0.5, v66
	v_mul_f32_e32 v66, 0x3fb8aa3b, v66
	v_exp_f32_e32 v66, v66
	s_nop 0
	v_xor_b32_e32 v72, 0x80000000, v66
	v_add_f32_e32 v66, v67, v83
	v_max_f32_e64 v67, -v66, 0
	v_mul_f32_e64 v66, |v66|, s21
	v_exp_f32_e32 v66, v66
	s_nop 0
	v_add_f32_e32 v66, 1.0, v66
	s_nop 1
	v_log_f32_e32 v66, v66
	s_nop 0
	v_mul_f32_e32 v70, 0x3f317217, v66
	v_fma_f32 v70, v66, s5, -v70
	v_fmac_f32_e32 v70, 0x3377d1cf, v66
	v_fmac_f32_e32 v70, 0x3f317217, v66
	s_nop 1
	v_mov_b32_e32 v66, v70
	v_add_f32_e32 v66, v67, v66
	v_sub_f32_e32 v66, -0.5, v66
	v_mul_f32_e32 v66, 0x3fb8aa3b, v66
	v_exp_f32_e32 v66, v66
	v_and_b32_e32 v67, 0xffff0000, v71
	v_xor_b32_e32 v73, 0x80000000, v66
	v_lshlrev_b32_e32 v66, 16, v71
	v_pk_add_f32 v[70:71], v[74:75], v[66:67] neg_lo:[0,1] neg_hi:[0,1]
	s_nop 0
	v_pk_fma_f32 v[214:215], v[70:71], v[78:79], v[66:67]
	v_rcp_f32_e32 v211, v63
	v_rcp_f32_e32 v210, v62
	s_nop 0
	v_pk_add_f32 v[62:63], v[210:211], -1.0 op_sel_hi:[1,0]
	s_nop 0
	v_pk_fma_f32 v[62:63], v[90:91], v[62:63], 1.0 op_sel_hi:[1,1,0]
	s_nop 0
	v_pk_mul_f32 v[62:63], v[214:215], v[62:63]
	s_nop 0
	v_pk_mul_f32 v[66:67], v[224:225], v[62:63]
	s_nop 0
	v_fmac_f32_e32 v139, v86, v66
	v_fmac_f32_e32 v139, v87, v67
	v_lshlrev_b32_e32 v66, 16, v40
	v_and_b32_e32 v67, 0xffff0000, v40
	v_pk_add_f32 v[48:49], v[48:49], v[66:67] neg_lo:[0,1] neg_hi:[0,1]
	v_lshlrev_b32_e32 v40, 16, v41
	v_and_b32_e32 v41, 0xffff0000, v41
	v_pk_fma_f32 v[44:45], v[44:45], v[48:49], v[66:67]
	v_pk_add_f32 v[48:49], v[50:51], v[40:41] neg_lo:[0,1] neg_hi:[0,1]
	s_nop 0
	v_pk_fma_f32 v[40:41], v[46:47], v[48:49], v[40:41]
	v_lshlrev_b32_e32 v46, 16, v42
	v_and_b32_e32 v47, 0xffff0000, v42
	v_pk_add_f32 v[36:37], v[36:37], v[46:47] neg_lo:[0,1] neg_hi:[0,1]
	s_nop 0
	v_pk_fma_f32 v[36:37], v[36:37], v[32:33], v[46:47]
	v_lshlrev_b32_e32 v32, 16, v43
	v_and_b32_e32 v33, 0xffff0000, v43
	v_pk_add_f32 v[38:39], v[38:39], v[32:33] neg_lo:[0,1] neg_hi:[0,1]
	s_nop 0
	v_pk_fma_f32 v[38:39], v[38:39], v[34:35], v[32:33]
	v_cvt_pk_bf16_f32 v32, v212, v213
	v_cvt_pk_bf16_f32 v33, v220, v221
	v_cvt_pk_bf16_f32 v34, v222, v223
	v_cvt_pk_bf16_f32 v35, v224, v225
	v_mad_i64_i32 v[212:213], s[0:1], v206, s20, v[170:171]
	global_store_dwordx4 v[212:213], v[32:35], off
	s_nop 1
	v_cvt_pk_bf16_f32 v32, v96, v97
	v_cvt_pk_bf16_f32 v33, v68, v69
	v_cvt_pk_bf16_f32 v34, v60, v61
	v_cvt_pk_bf16_f32 v35, v62, v63
	global_store_dwordx4 v[212:213], v[32:35], off offset:512
	s_nop 1
	v_cvt_pk_bf16_f32 v32, v44, v45
	v_cvt_pk_bf16_f32 v33, v40, v41
	v_cvt_pk_bf16_f32 v34, v36, v37
	v_cvt_pk_bf16_f32 v35, v38, v39
	global_store_dwordx4 v[212:213], v[32:35], off offset:1024
	s_nop 1
	v_cvt_pk_bf16_f32 v32, v100, v101
	v_cvt_pk_bf16_f32 v33, v102, v98
	v_cvt_pk_bf16_f32 v34, v64, v65
	v_cvt_pk_bf16_f32 v35, v72, v73
	global_store_dwordx4 v[212:213], v[32:35], off offset:2560
	s_nop 1
	v_cvt_pk_bf16_f32 v32, v52, v53
	v_cvt_pk_bf16_f32 v33, v54, v55
	v_cvt_pk_bf16_f32 v34, v56, v57
	v_cvt_pk_bf16_f32 v35, v58, v59
	global_store_dwordx4 v[216:217], v[32:35], off
	s_nop 1
	v_lshl_add_u64 v[32:33], v[208:209], 0, v[186:187]
	global_load_dwordx4 v[112:115], v[32:33], off
	global_load_dwordx4 v[116:119], v[218:219], off offset:144
	global_load_dwordx4 v[220:223], v[218:219], off offset:128
	global_load_dwordx4 v[120:123], v[158:159], off offset:144
	global_load_dwordx4 v[224:227], v[158:159], off offset:128
	v_lshl_add_u64 v[32:33], v[208:209], 0, v[188:189]
	global_load_dwordx4 v[56:59], v[32:33], off
	global_load_dwordx4 v[60:63], v[218:219], off offset:1168
	global_load_dwordx4 v[88:91], v[218:219], off offset:1152
	global_load_dwordx4 v[64:67], v[158:159], off offset:1168
	global_load_dwordx4 v[92:95], v[158:159], off offset:1152
	v_lshl_add_u64 v[32:33], v[208:209], 0, v[190:191]
	global_load_dwordx4 v[40:43], v[32:33], off
	global_load_dwordx4 v[36:39], v[218:219], off offset:2192
	global_load_dwordx4 v[48:51], v[218:219], off offset:2176
	s_nop 0
	global_load_dwordx4 v[32:35], v[158:159], off offset:2192
	global_load_dwordx4 v[44:47], v[158:159], off offset:2176
	global_load_dwordx4 v[68:71], v[160:161], off offset:144
	global_load_dwordx4 v[108:111], v[160:161], off offset:128
	global_load_dwordx4 v[72:75], v[162:163], off offset:144
	global_load_dwordx4 v[96:99], v[162:163], off offset:128
	global_load_dwordx4 v[76:79], v[164:165], off offset:144
	global_load_dwordx4 v[52:55], v[164:165], off offset:128
	global_load_dwordx4 v[84:87], v[166:167], off offset:144
	global_load_dwordx4 v[104:107], v[166:167], off offset:128
	global_load_dwordx4 v[80:83], v[168:169], off offset:144
	global_load_dwordx4 v[100:103], v[168:169], off offset:128
	s_waitcnt vmcnt(0)
	v_add_f32_e32 v20, v20, v68
	v_add_f32_e32 v28, v28, v108
	v_max_f32_e64 v108, -v28, 0
	v_mul_f32_e64 v28, |v28|, s21
	v_exp_f32_e32 v28, v28
	s_waitcnt lgkmcnt(0)
	v_lshlrev_b32_e32 v208, 16, v112
	v_and_b32_e32 v209, 0xffff0000, v112
	v_pk_add_f32 v[218:219], v[220:221], v[208:209] neg_lo:[0,1] neg_hi:[0,1]
	v_lshlrev_b32_e32 v112, 16, v113
	v_and_b32_e32 v113, 0xffff0000, v113
	v_pk_fma_f32 v[208:209], v[218:219], v[224:225], v[208:209]
	v_pk_add_f32 v[218:219], v[222:223], v[112:113] neg_lo:[0,1] neg_hi:[0,1]
	v_add_f32_e32 v28, 1.0, v28
	v_pk_fma_f32 v[112:113], v[218:219], v[226:227], v[112:113]
	v_lshlrev_b32_e32 v218, 16, v114
	v_and_b32_e32 v219, 0xffff0000, v114
	v_lshlrev_b32_e32 v114, 16, v115
	v_and_b32_e32 v115, 0xffff0000, v115
	v_pk_add_f32 v[118:119], v[118:119], v[114:115] neg_lo:[0,1] neg_hi:[0,1]
	s_nop 0
	v_pk_fma_f32 v[114:115], v[118:119], v[122:123], v[114:115]
	v_add_f32_e32 v24, v24, v96
	v_log_f32_e32 v28, v28
	v_add_f32_e32 v25, v25, v97
	v_mul_f32_e32 v24, 0xbfb8aa3b, v24
	v_mul_f32_e32 v25, 0xbfb8aa3b, v25
	v_mul_f32_e32 v118, 0x3f317217, v28
	v_fma_f32 v118, v28, s5, -v118
	v_fmac_f32_e32 v118, 0x3377d1cf, v28
	v_fmac_f32_e32 v118, 0x3f317217, v28
	v_exp_f32_e32 v24, v24
	v_exp_f32_e32 v25, v25
	v_mov_b32_e32 v28, v118
	v_add_f32_e32 v28, v108, v28
	v_sub_f32_e32 v28, -0.5, v28
	v_mul_f32_e32 v28, 0x3fb8aa3b, v28
	v_exp_f32_e32 v28, v28
	v_pk_add_f32 v[24:25], v[24:25], 1.0 op_sel_hi:[1,0]
	v_add_f32_e32 v30, v30, v110
	v_add_f32_e32 v26, v26, v98
	v_xor_b32_e32 v108, 0x80000000, v28
	v_add_f32_e32 v28, v29, v109
	v_max_f32_e64 v29, -v28, 0
	v_mul_f32_e64 v28, |v28|, s21
	v_exp_f32_e32 v28, v28
	v_add_f32_e32 v27, v27, v99
	v_mul_f32_e32 v26, 0xbfb8aa3b, v26
	v_mul_f32_e32 v27, 0xbfb8aa3b, v27
	v_add_f32_e32 v28, 1.0, v28
	v_exp_f32_e32 v26, v26
	v_exp_f32_e32 v27, v27
	v_log_f32_e32 v28, v28
	v_pk_add_f32 v[26:27], v[26:27], 1.0 op_sel_hi:[1,0]
	v_max_f32_e64 v68, -v20, 0
	v_mul_f32_e64 v20, |v20|, s21
	v_mul_f32_e32 v96, 0x3f317217, v28
	v_fma_f32 v96, v28, s5, -v96
	v_fmac_f32_e32 v96, 0x3377d1cf, v28
	v_fmac_f32_e32 v96, 0x3f317217, v28
	v_exp_f32_e32 v20, v20
	v_add_f32_e32 v16, v16, v72
	v_mov_b32_e32 v28, v96
	v_add_f32_e32 v28, v29, v28
	v_sub_f32_e32 v28, -0.5, v28
	v_mul_f32_e32 v28, 0x3fb8aa3b, v28
	v_exp_f32_e32 v28, v28
	v_and_b32_e32 v29, 0xffff0000, v56
	v_add_f32_e32 v20, 1.0, v20
	v_add_f32_e32 v17, v17, v73
	v_xor_b32_e32 v96, 0x80000000, v28
	v_lshlrev_b32_e32 v28, 16, v56
	v_pk_add_f32 v[88:89], v[88:89], v[28:29] neg_lo:[0,1] neg_hi:[0,1]
	s_nop 0
	v_pk_fma_f32 v[28:29], v[92:93], v[88:89], v[28:29]
	v_mul_f32_e32 v16, 0xbfb8aa3b, v16
	v_mul_f32_e32 v17, 0xbfb8aa3b, v17
	v_exp_f32_e32 v16, v16
	v_rcp_f32_e32 v25, v25
	v_exp_f32_e32 v17, v17
	v_add_f32_e32 v22, v22, v70
	v_add_f32_e32 v18, v18, v74
	v_rcp_f32_e32 v24, v24
	v_max_f32_e64 v56, -v30, 0
	v_mul_f32_e64 v30, |v30|, s21
	v_exp_f32_e32 v30, v30
	v_pk_add_f32 v[88:89], v[24:25], -1.0 op_sel_hi:[1,0]
	v_pk_add_f32 v[16:17], v[16:17], 1.0 op_sel_hi:[1,0]
	v_pk_fma_f32 v[88:89], v[104:105], v[88:89], 1.0 op_sel_hi:[1,1,0]
	v_add_f32_e32 v30, 1.0, v30
	v_pk_mul_f32 v[88:89], v[28:29], v[88:89]
	s_nop 0
	v_pk_mul_f32 v[92:93], v[208:209], v[88:89]
	v_add_f32_e32 v19, v19, v75
	v_fmac_f32_e32 v139, v100, v92
	v_log_f32_e32 v30, v30
	v_fmac_f32_e32 v139, v101, v93
	v_mul_f32_e32 v18, 0xbfb8aa3b, v18
	v_mul_f32_e32 v19, 0xbfb8aa3b, v19
	v_mul_f32_e32 v92, 0x3f317217, v30
	v_fma_f32 v92, v30, s5, -v92
	v_fmac_f32_e32 v92, 0x3377d1cf, v30
	v_fmac_f32_e32 v92, 0x3f317217, v30
	v_exp_f32_e32 v18, v18
	v_exp_f32_e32 v19, v19
	v_mov_b32_e32 v30, v92
	v_add_f32_e32 v30, v56, v30
	v_sub_f32_e32 v30, -0.5, v30
	v_mul_f32_e32 v30, 0x3fb8aa3b, v30
	v_exp_f32_e32 v30, v30
	v_pk_add_f32 v[18:19], v[18:19], 1.0 op_sel_hi:[1,0]
	v_pk_add_f32 v[116:117], v[116:117], v[218:219] neg_lo:[0,1] neg_hi:[0,1]
	v_pk_mul_f32 v[28:29], v[28:29], v[52:53]
	v_xor_b32_e32 v92, 0x80000000, v30
	v_add_f32_e32 v30, v31, v111
	v_max_f32_e64 v31, -v30, 0
	v_mul_f32_e64 v30, |v30|, s21
	v_exp_f32_e32 v30, v30
	v_pk_fma_f32 v[116:117], v[116:117], v[120:121], v[218:219]
	v_add_f32_e32 v30, 1.0, v30
	s_nop 1
	v_log_f32_e32 v30, v30
	s_nop 0
	v_mul_f32_e32 v56, 0x3f317217, v30
	v_fma_f32 v56, v30, s5, -v56
	v_fmac_f32_e32 v56, 0x3377d1cf, v30
	v_fmac_f32_e32 v56, 0x3f317217, v30
	s_nop 1
	v_mov_b32_e32 v30, v56
	v_add_f32_e32 v30, v31, v30
	v_sub_f32_e32 v30, -0.5, v30
	v_mul_f32_e32 v30, 0x3fb8aa3b, v30
	v_exp_f32_e32 v30, v30
	v_and_b32_e32 v31, 0xffff0000, v57
	v_xor_b32_e32 v93, 0x80000000, v30
	v_lshlrev_b32_e32 v30, 16, v57
	v_pk_add_f32 v[56:57], v[90:91], v[30:31] neg_lo:[0,1] neg_hi:[0,1]
	s_nop 0
	v_pk_fma_f32 v[30:31], v[94:95], v[56:57], v[30:31]
	v_rcp_f32_e32 v27, v27
	v_rcp_f32_e32 v26, v26
	s_nop 0
	v_pk_add_f32 v[56:57], v[26:27], -1.0 op_sel_hi:[1,0]
	s_nop 0
	v_pk_fma_f32 v[56:57], v[106:107], v[56:57], 1.0 op_sel_hi:[1,1,0]
	s_nop 0
	v_pk_mul_f32 v[56:57], v[30:31], v[56:57]
	v_pk_mul_f32 v[30:31], v[30:31], v[54:55]
	v_pk_mul_f32 v[90:91], v[112:113], v[56:57]
	v_pk_mul_f32 v[54:55], v[30:31], v[30:31]
	v_fmac_f32_e32 v139, v102, v90
	v_log_f32_e32 v20, v20
	v_fmac_f32_e32 v139, v103, v91
	v_mul_f32_e32 v90, 0x3f317217, v20
	v_fma_f32 v90, v20, s5, -v90
	v_fmac_f32_e32 v90, 0x3377d1cf, v20
	v_fmac_f32_e32 v90, 0x3f317217, v20
	s_nop 1
	v_mov_b32_e32 v20, v90
	v_add_f32_e32 v20, v68, v20
	v_sub_f32_e32 v20, -0.5, v20
	v_mul_f32_e32 v20, 0x3fb8aa3b, v20
	v_exp_f32_e32 v20, v20
	s_nop 0
	v_xor_b32_e32 v68, 0x80000000, v20
	v_add_f32_e32 v20, v21, v69
	v_max_f32_e64 v21, -v20, 0
	v_mul_f32_e64 v20, |v20|, s21
	v_exp_f32_e32 v20, v20
	s_nop 0
	v_add_f32_e32 v20, 1.0, v20
	s_nop 1
	v_log_f32_e32 v20, v20
	s_nop 0
	v_mul_f32_e32 v69, 0x3f317217, v20
	v_fma_f32 v69, v20, s5, -v69
	v_fmac_f32_e32 v69, 0x3377d1cf, v20
	v_fmac_f32_e32 v69, 0x3f317217, v20
	s_nop 1
	v_mov_b32_e32 v20, v69
	v_add_f32_e32 v20, v21, v20
	v_sub_f32_e32 v20, -0.5, v20
	v_mul_f32_e32 v20, 0x3fb8aa3b, v20
	v_exp_f32_e32 v20, v20
	v_and_b32_e32 v21, 0xffff0000, v58
	v_xor_b32_e32 v69, 0x80000000, v20
	v_lshlrev_b32_e32 v20, 16, v58
	v_pk_add_f32 v[60:61], v[60:61], v[20:21] neg_lo:[0,1] neg_hi:[0,1]
	s_nop 0
	v_pk_fma_f32 v[20:21], v[60:61], v[64:65], v[20:21]
	v_rcp_f32_e32 v17, v17
	v_rcp_f32_e32 v16, v16
	v_max_f32_e64 v58, -v22, 0
	v_mul_f32_e64 v22, |v22|, s21
	v_exp_f32_e32 v22, v22
	v_pk_add_f32 v[60:61], v[16:17], -1.0 op_sel_hi:[1,0]
	v_add_f32_e32 v22, 1.0, v22
	v_pk_fma_f32 v[60:61], v[84:85], v[60:61], 1.0 op_sel_hi:[1,1,0]
	s_nop 0
	v_log_f32_e32 v22, v22
	v_pk_mul_f32 v[64:65], v[20:21], v[60:61]
	v_pk_mul_f32 v[20:21], v[20:21], v[76:77]
	v_pk_mul_f32 v[72:73], v[116:117], v[64:65]
	v_mul_f32_e32 v70, 0x3f317217, v22
	v_fma_f32 v70, v22, s5, -v70
	v_fmac_f32_e32 v70, 0x3377d1cf, v22
	v_fmac_f32_e32 v70, 0x3f317217, v22
	v_fmac_f32_e32 v139, v80, v72
	v_fmac_f32_e32 v139, v81, v73
	v_mov_b32_e32 v22, v70
	v_add_f32_e32 v22, v58, v22
	v_sub_f32_e32 v22, -0.5, v22
	v_mul_f32_e32 v22, 0x3fb8aa3b, v22
	v_exp_f32_e32 v22, v22
	v_pk_mul_f32 v[60:61], v[20:21], v[20:21]
	v_xor_b32_e32 v70, 0x80000000, v22
	v_add_f32_e32 v22, v23, v71
	v_max_f32_e64 v23, -v22, 0
	v_mul_f32_e64 v22, |v22|, s21
	v_exp_f32_e32 v22, v22
	s_nop 0
	v_add_f32_e32 v22, 1.0, v22
	s_nop 1
	v_log_f32_e32 v22, v22
	s_nop 0
	v_mul_f32_e32 v58, 0x3f317217, v22
	v_fma_f32 v58, v22, s5, -v58
	v_fmac_f32_e32 v58, 0x3377d1cf, v22
	v_fmac_f32_e32 v58, 0x3f317217, v22
	s_nop 1
	v_mov_b32_e32 v22, v58
	v_add_f32_e32 v22, v23, v22
	v_sub_f32_e32 v22, -0.5, v22
	v_mul_f32_e32 v22, 0x3fb8aa3b, v22
	v_exp_f32_e32 v22, v22
	v_and_b32_e32 v23, 0xffff0000, v59
	v_xor_b32_e32 v71, 0x80000000, v22
	v_lshlrev_b32_e32 v22, 16, v59
	v_pk_add_f32 v[58:59], v[62:63], v[22:23] neg_lo:[0,1] neg_hi:[0,1]
	s_nop 0
	v_pk_fma_f32 v[22:23], v[58:59], v[66:67], v[22:23]
	v_rcp_f32_e32 v19, v19
	v_rcp_f32_e32 v18, v18
	s_nop 0
	v_pk_add_f32 v[58:59], v[18:19], -1.0 op_sel_hi:[1,0]
	s_nop 0
	v_pk_fma_f32 v[58:59], v[86:87], v[58:59], 1.0 op_sel_hi:[1,1,0]
	s_nop 0
	v_pk_mul_f32 v[58:59], v[22:23], v[58:59]
	v_pk_mul_f32 v[22:23], v[22:23], v[78:79]
	v_pk_mul_f32 v[62:63], v[114:115], v[58:59]
	v_pk_mul_f32 v[66:67], v[22:23], v[22:23]
	v_fmac_f32_e32 v139, v82, v62
	v_fmac_f32_e32 v139, v83, v63
	v_lshlrev_b32_e32 v62, 16, v40
	v_and_b32_e32 v63, 0xffff0000, v40
	v_pk_add_f32 v[48:49], v[48:49], v[62:63] neg_lo:[0,1] neg_hi:[0,1]
	v_lshlrev_b32_e32 v40, 16, v41
	v_and_b32_e32 v41, 0xffff0000, v41
	v_pk_fma_f32 v[44:45], v[44:45], v[48:49], v[62:63]
	v_pk_add_f32 v[48:49], v[50:51], v[40:41] neg_lo:[0,1] neg_hi:[0,1]
	s_nop 0
	v_pk_fma_f32 v[40:41], v[46:47], v[48:49], v[40:41]
	v_lshlrev_b32_e32 v46, 16, v42
	v_and_b32_e32 v47, 0xffff0000, v42
	v_pk_add_f32 v[36:37], v[36:37], v[46:47] neg_lo:[0,1] neg_hi:[0,1]
	s_nop 0
	v_pk_fma_f32 v[36:37], v[36:37], v[32:33], v[46:47]
	v_lshlrev_b32_e32 v32, 16, v43
	v_and_b32_e32 v33, 0xffff0000, v43
	v_pk_add_f32 v[38:39], v[38:39], v[32:33] neg_lo:[0,1] neg_hi:[0,1]
	s_nop 0
	v_pk_fma_f32 v[38:39], v[38:39], v[34:35], v[32:33]
	v_cvt_pk_bf16_f32 v32, v208, v209
	v_cvt_pk_bf16_f32 v33, v112, v113
	v_cvt_pk_bf16_f32 v34, v116, v117
	v_cvt_pk_bf16_f32 v35, v114, v115
	global_store_dwordx4 v[212:213], v[32:35], off offset:64
	s_nop 1
	v_cvt_pk_bf16_f32 v32, v88, v89
	v_cvt_pk_bf16_f32 v33, v56, v57
	v_cvt_pk_bf16_f32 v34, v64, v65
	v_cvt_pk_bf16_f32 v35, v58, v59
	global_store_dwordx4 v[212:213], v[32:35], off offset:576
	s_nop 1
	v_cvt_pk_bf16_f32 v32, v44, v45
	v_cvt_pk_bf16_f32 v33, v40, v41
	v_cvt_pk_bf16_f32 v34, v36, v37
	v_cvt_pk_bf16_f32 v35, v38, v39
	global_store_dwordx4 v[212:213], v[32:35], off offset:1088
	s_nop 1
	v_cvt_pk_bf16_f32 v32, v108, v96
	v_cvt_pk_bf16_f32 v33, v92, v93
	v_cvt_pk_bf16_f32 v34, v68, v69
	v_cvt_pk_bf16_f32 v35, v70, v71
	global_store_dwordx4 v[212:213], v[32:35], off offset:2624
	global_store_dwordx4 v[216:217], v[0:3], off offset:64
	s_nop 0
	v_pk_mul_f32 v[32:33], v[8:9], v[8:9]
	v_pk_mul_f32 v[2:3], v[214:215], v[14:15]
	v_pk_mul_f32 v[14:15], v[10:11], v[10:11]
	v_add_f32_e32 v32, v32, v33
	v_add_f32_e32 v14, v14, v32
	v_add_f32_e32 v14, v15, v14
	v_add_f32_e32 v12, v14, v12
	v_pk_mul_f32 v[4:5], v[2:3], v[2:3]
	v_add_f32_e32 v12, v13, v12
	v_add_f32_e32 v4, v4, v12
	v_pk_mul_f32 v[34:35], v[28:29], v[28:29]
	v_add_f32_e32 v4, v5, v4
	v_add_f32_e32 v4, v4, v34
	v_add_f32_e32 v4, v35, v4
	v_add_f32_e32 v4, v54, v4
	v_and_b32_e32 v1, 64, v243
	v_add_f32_e32 v4, v55, v4
	v_xor_b32_e32 v0, 16, v243
	v_add_u32_e32 v1, 64, v1
	v_add_f32_e32 v4, v4, v60
	v_cmp_lt_i32_e32 vcc, v0, v1
	v_add_f32_e32 v4, v61, v4
	v_add_f32_e32 v4, v66, v4
	v_cndmask_b32_e32 v0, v243, v0, vcc
	v_lshlrev_b32_e32 v36, 2, v0
	v_add_f32_e32 v4, v67, v4
	ds_bpermute_b32 v5, v36, v4
	v_xor_b32_e32 v0, 32, v243
	v_cmp_lt_i32_e32 vcc, v0, v1
	s_waitcnt lgkmcnt(0)
	v_add_f32_e32 v4, v4, v5
	v_cndmask_b32_e32 v0, v243, v0, vcc
	v_lshlrev_b32_e32 v37, 2, v0
	ds_bpermute_b32 v5, v37, v4
	ds_bpermute_b32 v0, v36, v139
	s_waitcnt lgkmcnt(0)
	v_add_f32_e32 v4, v4, v5
	v_cmp_gt_f32_e32 vcc, s34, v4
	v_mul_f32_e32 v5, 0x4f800000, v4
	v_add_f32_e32 v0, v139, v0
	v_cndmask_b32_e32 v4, v4, v5, vcc
	v_sqrt_f32_e32 v5, v4
	ds_bpermute_b32 v1, v37, v0
	v_add_u32_e32 v12, -1, v5
	v_fma_f32 v13, -v12, v5, v4
	v_cmp_ge_f32_e64 s[0:1], 0, v13
	v_add_u32_e32 v13, 1, v5
	s_nop 0
	v_cndmask_b32_e64 v12, v5, v12, s[0:1]
	v_fma_f32 v5, -v13, v5, v4
	v_cmp_lt_f32_e64 s[0:1], 0, v5
	s_nop 1
	v_cndmask_b32_e64 v5, v12, v13, s[0:1]
	v_mul_f32_e32 v12, 0x37800000, v5
	v_cndmask_b32_e32 v5, v5, v12, vcc
	v_cmp_class_f32_e32 vcc, v4, v237
	s_nop 1
	v_cndmask_b32_e32 v4, v5, v4, vcc
	v_max_f32_e32 v4, 0x2b8cbccc, v4
	v_rcp_f32_e32 v12, v4
	s_nop 0
	v_pk_mul_f32 v[4:5], v[8:9], v[12:13] op_sel_hi:[1,0]
	v_pk_mul_f32 v[10:11], v[10:11], v[12:13] op_sel_hi:[1,0]
	v_pk_mul_f32 v[6:7], v[6:7], v[12:13] op_sel_hi:[1,0]
	v_pk_mul_f32 v[34:35], v[2:3], v[12:13] op_sel_hi:[1,0]
	v_pk_mul_f32 v[8:9], v[124:125], v[4:5]
	v_pk_mul_f32 v[14:15], v[126:127], v[10:11]
	v_pk_mul_f32 v[32:33], v[132:133], v[6:7]
	v_pk_mul_f32 v[36:37], v[210:211], v[34:35]
	v_cvt_pk_bf16_f32 v2, v4, v5
	v_cvt_pk_bf16_f32 v3, v10, v11
	v_cvt_pk_bf16_f32 v4, v6, v7
	v_cvt_pk_bf16_f32 v5, v34, v35
	global_store_dwordx4 v[212:213], v[2:5], off offset:1536
	v_pk_mul_f32 v[10:11], v[20:21], v[12:13] op_sel_hi:[1,0]
	s_nop 0
	v_cvt_pk_bf16_f32 v2, v8, v9
	v_cvt_pk_bf16_f32 v3, v14, v15
	v_cvt_pk_bf16_f32 v4, v32, v33
	v_cvt_pk_bf16_f32 v5, v36, v37
	global_store_dwordx4 v[212:213], v[2:5], off offset:2048
	v_pk_mul_f32 v[14:15], v[16:17], v[10:11]
	s_nop 0
	v_pk_mul_f32 v[2:3], v[28:29], v[12:13] op_sel_hi:[1,0]
	v_pk_mul_f32 v[4:5], v[30:31], v[12:13] op_sel_hi:[1,0]
	v_pk_mul_f32 v[12:13], v[22:23], v[12:13] op_sel_hi:[1,0]
	v_pk_mul_f32 v[6:7], v[24:25], v[2:3]
	v_pk_mul_f32 v[8:9], v[26:27], v[4:5]
	v_pk_mul_f32 v[16:17], v[18:19], v[12:13]
	v_cvt_pk_bf16_f32 v2, v2, v3
	v_cvt_pk_bf16_f32 v3, v4, v5
	v_cvt_pk_bf16_f32 v4, v10, v11
	v_cvt_pk_bf16_f32 v5, v12, v13
	global_store_dwordx4 v[212:213], v[2:5], off offset:1600
	s_nop 1
	v_cvt_pk_bf16_f32 v2, v6, v7
	v_cvt_pk_bf16_f32 v3, v8, v9
	v_cvt_pk_bf16_f32 v4, v14, v15
	v_cvt_pk_bf16_f32 v5, v16, v17
	global_store_dwordx4 v[212:213], v[2:5], off offset:2112
	s_and_saveexec_b64 s[0:1], s[8:9]
	s_cbranch_execz .LBB0_346
	v_lshl_add_u64 v[2:3], v[206:207], 4, s[12:13]
	s_waitcnt lgkmcnt(0)
	v_add_f32_e32 v0, v0, v1
	global_store_dword v[2:3], v0, off
	s_branch .LBB0_346
